# out-proj and down-proj: last K-iteration peeled (no re-read staging), 10 of 16 residual row loads prefetched there into loop-free registers
# speedup vs baseline: 1.0079x; 1.0040x over previous
; #define PG8_STAGE(bufoff, gbase, voff) do { _Pragma("unroll") for (int _i = 0; _i < 2; ++_i) \
;         __builtin_amdgcn_global_load_lds((const unsigned*)((const char*)(gbase) + (voff)[_i]), (PG8_LAS unsigned*)(lds + (bufoff) + ldsw + _i * 8192), 16, 0, 0); } while (0)
; #define PG8_LDA(dst, b, h) do { _Pragma("unroll") for (int m = 0; m < 4; ++m) _Pragma("unroll") for (int k = 0; k < 2; ++k) dst[m][k] = *(const PG8_LAS bf16x8*)(lds + PG8_SA(b, h) + aoff + m * 2048 + k * 1024); } while (0)
; #define PG8_LDB(dst, b, h) do { _Pragma("unroll") for (int n = 0; n < 2; ++n) _Pragma("unroll") for (int k = 0; k < 2; ++k) dst[n][k] = *(const PG8_LAS bf16x8*)(lds + PG8_SB(b, h) + boff + n * 2048 + k * 1024); } while (0)
; #define PG8_MMA(ai, bj, At, Bt) do { __builtin_amdgcn_s_setprio(1); _Pragma("unroll") for (int m = 0; m < 4; ++m) _Pragma("unroll") for (int n = 0; n < 2; ++n) _Pragma("unroll") for (int k = 0; k < 2; ++k) \
;         acc[ai][bj][m][n] = __builtin_amdgcn_mfma_f32_16x16x32_bf16(Bt[n][k], At[m][k], acc[ai][bj][m][n], 0, 0, 0); __builtin_amdgcn_s_setprio(0); } while (0)
; #define PG8_WAIT_V(n) asm volatile("s_waitcnt vmcnt(" #n ")" ::: "memory")
; #define PG8_WAIT_L(n) asm volatile("s_waitcnt lgkmcnt(" #n ")" ::: "memory")
; #define PG8_BAR __builtin_amdgcn_s_barrier()
; #define PG8_SCHED __builtin_amdgcn_sched_barrier(0)
; template <class Epi, class Sched, bool ALIGN_EPI = false, bool SP2 = false>
; __device__ __forceinline__ void gemm_phase(PG8_LAS unsigned char* lds, const Gemm g, const Sched& S, const Epi& E) {
;     ...
;             PG8_LDB(B0, 0, 0); PG8_LDB(B1, 0, 1); PG8_SCHED; PG8_LDA(At, 0, 0); PG8_STAGE(PG8_SA(1, 1), a1 + hstep, voffA);
;             PG8_WAIT_V(8); PG8_WAIT_L(0); PG8_BAR; PG8_MMA(0, 0, At, B0); PG8_MMA(0, 1, At, B1); PG8_BAR; PG8_SCHED;
;             PG8_LDA(At, 0, 1); PG8_STAGE(PG8_SB(0, 0), b2, voffB); PG8_STAGE(PG8_SB(0, 1), b2 + hstep, voffB); PG8_STAGE(PG8_SA(0, 0), a2, voffA);
;             PG8_WAIT_V(8); PG8_WAIT_L(0); PG8_BAR; PG8_MMA(1, 0, At, B0); PG8_MMA(1, 1, At, B1); PG8_BAR; PG8_SCHED;
.LBB0_609:
	ds_read_b128 v[98:101], v239
	ds_read_b128 v[110:113], v239 offset:1024
	ds_read_b128 v[122:125], v239 offset:2048
	ds_read_b128 v[134:137], v239 offset:3072
	ds_read_b128 v[138:141], v240
	ds_read_b128 v[142:145], v240 offset:1024
	ds_read_b128 v[146:149], v240 offset:2048
	ds_read_b128 v[150:153], v240 offset:3072
	s_add_u32 s18, s40, 0xfffc0080
	s_addc_u32 s19, s41, -1
	s_cmp_eq_u32 s62, 12
	s_cselect_b32 s43, s27, s19
	s_cselect_b32 s42, s39, s18
	s_cselect_b32 s31, s17, s61
	s_cselect_b32 s30, s59, s60
	v_lshl_add_u64 v[208:209], s[40:41], 0, v[198:199]
	s_add_i32 m0, s45, 0xc000
	ds_read_b128 v[162:165], v241
	ds_read_b128 v[166:169], v241 offset:1024
	ds_read_b128 v[170:173], v241 offset:2048
	ds_read_b128 v[174:177], v241 offset:3072
	ds_read_b128 v[178:181], v241 offset:4096
	ds_read_b128 v[182:185], v241 offset:5120
	ds_read_b128 v[186:189], v241 offset:6144
	ds_read_b128 v[204:207], v241 offset:7168
	global_load_lds_dwordx4 v[208:209], off
	v_lshl_add_u64 v[208:209], s[40:41], 0, v[200:201]
	s_add_i32 m0, s45, 0xe000
	s_nop 0
	global_load_lds_dwordx4 v[208:209], off
	s_waitcnt vmcnt(8)
	s_waitcnt lgkmcnt(0)
	s_barrier
	s_setprio 1
	s_waitcnt lgkmcnt(0)
	v_mfma_f32_16x16x32_bf16 v[158:161], v[98:101], v[162:165], v[158:161]
	v_mfma_f32_16x16x32_bf16 v[154:157], v[122:125], v[162:165], v[154:157]
	v_mfma_f32_16x16x32_bf16 v[118:121], v[98:101], v[170:173], v[118:121]
	v_mfma_f32_16x16x32_bf16 v[114:117], v[122:125], v[170:173], v[114:117]
	v_mfma_f32_16x16x32_bf16 v[94:97], v[98:101], v[178:181], v[94:97]
	v_mfma_f32_16x16x32_bf16 v[90:93], v[122:125], v[178:181], v[90:93]
	v_mfma_f32_16x16x32_bf16 v[78:81], v[98:101], v[186:189], v[78:81]
	v_mfma_f32_16x16x32_bf16 v[74:77], v[122:125], v[186:189], v[74:77]
	v_mfma_f32_16x16x32_bf16 v[158:161], v[110:113], v[166:169], v[158:161]
	v_mfma_f32_16x16x32_bf16 v[154:157], v[134:137], v[166:169], v[154:157]
	v_mfma_f32_16x16x32_bf16 v[118:121], v[110:113], v[174:177], v[118:121]
	v_mfma_f32_16x16x32_bf16 v[114:117], v[134:137], v[174:177], v[114:117]
	v_mfma_f32_16x16x32_bf16 v[94:97], v[110:113], v[182:185], v[94:97]
	v_mfma_f32_16x16x32_bf16 v[90:93], v[134:137], v[182:185], v[90:93]
	v_mfma_f32_16x16x32_bf16 v[78:81], v[110:113], v[204:207], v[78:81]
	v_mfma_f32_16x16x32_bf16 v[74:77], v[134:137], v[204:207], v[74:77]
	s_setprio 0
	s_setprio 1
	v_mfma_f32_16x16x32_bf16 v[130:133], v[138:141], v[162:165], v[130:133]
	v_mfma_f32_16x16x32_bf16 v[126:129], v[146:149], v[162:165], v[126:129]
	v_mfma_f32_16x16x32_bf16 v[106:109], v[138:141], v[170:173], v[106:109]
	v_mfma_f32_16x16x32_bf16 v[102:105], v[146:149], v[170:173], v[102:105]
	v_mfma_f32_16x16x32_bf16 v[86:89], v[138:141], v[178:181], v[86:89]
	v_mfma_f32_16x16x32_bf16 v[82:85], v[146:149], v[178:181], v[82:85]
	v_mfma_f32_16x16x32_bf16 v[70:73], v[138:141], v[186:189], v[70:73]
	v_mfma_f32_16x16x32_bf16 v[66:69], v[146:149], v[186:189], v[66:69]
	v_mfma_f32_16x16x32_bf16 v[130:133], v[142:145], v[166:169], v[130:133]
	v_mfma_f32_16x16x32_bf16 v[126:129], v[150:153], v[166:169], v[126:129]
	v_mfma_f32_16x16x32_bf16 v[106:109], v[142:145], v[174:177], v[106:109]
	v_mfma_f32_16x16x32_bf16 v[102:105], v[150:153], v[174:177], v[102:105]
	v_mfma_f32_16x16x32_bf16 v[86:89], v[142:145], v[182:185], v[86:89]
	v_mfma_f32_16x16x32_bf16 v[82:85], v[150:153], v[182:185], v[82:85]
	v_mfma_f32_16x16x32_bf16 v[70:73], v[142:145], v[204:207], v[70:73]
	v_mfma_f32_16x16x32_bf16 v[66:69], v[150:153], v[204:207], v[66:69]
	s_setprio 0
	s_barrier
	s_add_i32 s18, s56, s44
	v_lshl_add_u64 v[208:209], s[30:31], 0, v[192:193]
	s_mov_b32 m0, s18
	ds_read_b128 v[162:165], v241 offset:16384
	ds_read_b128 v[166:169], v241 offset:17408
	ds_read_b128 v[170:173], v241 offset:18432
	ds_read_b128 v[174:177], v241 offset:19456
	ds_read_b128 v[178:181], v241 offset:20480
	ds_read_b128 v[182:185], v241 offset:21504
	ds_read_b128 v[186:189], v241 offset:22528
	ds_read_b128 v[204:207], v241 offset:23552
	global_load_lds_dwordx4 v[208:209], off
	s_add_i32 m0, s18, 0x2000
	s_add_u32 s18, s30, 0x40000
	v_lshl_add_u64 v[210:211], s[30:31], 0, v[196:197]
	s_addc_u32 s19, s31, 0
	s_add_i32 s63, s57, s44
	global_load_lds_dwordx4 v[210:211], off
	v_lshl_add_u64 v[212:213], s[18:19], 0, v[192:193]
	s_mov_b32 m0, s63
	v_lshl_add_u64 v[214:215], s[42:43], 0, v[194:195]
	global_load_lds_dwordx4 v[212:213], off
	v_lshl_add_u64 v[212:213], s[18:19], 0, v[196:197]
	s_add_i32 m0, s63, 0x2000
	s_nop 0
	global_load_lds_dwordx4 v[212:213], off
	v_lshl_add_u64 v[212:213], s[42:43], 0, v[190:191]
	s_mov_b32 m0, s45
	s_nop 0
	global_load_lds_dwordx4 v[212:213], off
	s_mov_b32 m0, s46
	s_nop 0
	global_load_lds_dwordx4 v[214:215], off
	s_waitcnt vmcnt(8)
	s_waitcnt lgkmcnt(0)
	s_barrier
; #define PG8_STAGE(bufoff, gbase, voff) do { _Pragma("unroll") for (int _i = 0; _i < 2; ++_i) \
;         __builtin_amdgcn_global_load_lds((const unsigned*)((const char*)(gbase) + (voff)[_i]), (PG8_LAS unsigned*)(lds + (bufoff) + ldsw + _i * 8192), 16, 0, 0); } while (0)
; #define PG8_LDA(dst, b, h) do { _Pragma("unroll") for (int m = 0; m < 4; ++m) _Pragma("unroll") for (int k = 0; k < 2; ++k) dst[m][k] = *(const PG8_LAS bf16x8*)(lds + PG8_SA(b, h) + aoff + m * 2048 + k * 1024); } while (0)
; #define PG8_LDB(dst, b, h) do { _Pragma("unroll") for (int n = 0; n < 2; ++n) _Pragma("unroll") for (int k = 0; k < 2; ++k) dst[n][k] = *(const PG8_LAS bf16x8*)(lds + PG8_SB(b, h) + boff + n * 2048 + k * 1024); } while (0)
; #define PG8_MMA(ai, bj, At, Bt) do { __builtin_amdgcn_s_setprio(1); _Pragma("unroll") for (int m = 0; m < 4; ++m) _Pragma("unroll") for (int n = 0; n < 2; ++n) _Pragma("unroll") for (int k = 0; k < 2; ++k) \
;         acc[ai][bj][m][n] = __builtin_amdgcn_mfma_f32_16x16x32_bf16(Bt[n][k], At[m][k], acc[ai][bj][m][n], 0, 0, 0); __builtin_amdgcn_s_setprio(0); } while (0)
; #define PG8_WAIT_V(n) asm volatile("s_waitcnt vmcnt(" #n ")" ::: "memory")
; #define PG8_WAIT_L(n) asm volatile("s_waitcnt lgkmcnt(" #n ")" ::: "memory")
; #define PG8_BAR __builtin_amdgcn_s_barrier()
; #define PG8_SCHED __builtin_amdgcn_sched_barrier(0)
; template <class Epi, class Sched, bool ALIGN_EPI = false, bool SP2 = false>
; __device__ __forceinline__ void gemm_phase(PG8_LAS unsigned char* lds, const Gemm g, const Sched& S, const Epi& E) {
;     ...
;             PG8_WAIT_V(8); PG8_WAIT_L(0); PG8_BAR; PG8_MMA(1, 0, At, B0); PG8_MMA(1, 1, At, B1); PG8_BAR; PG8_SCHED;
;             PG8_LDB(B0, 1, 0); PG8_LDB(B1, 1, 1); PG8_SCHED; PG8_LDA(At, 1, 0); PG8_STAGE(PG8_SA(0, 1), a2 + hstep, voffA);
;             PG8_WAIT_V(8); PG8_WAIT_L(0); PG8_BAR; PG8_MMA(0, 0, At, B0); PG8_MMA(0, 1, At, B1); PG8_BAR; PG8_SCHED;
	s_setprio 1
	s_waitcnt lgkmcnt(0)
	v_mfma_f32_16x16x32_bf16 v[62:65], v[98:101], v[162:165], v[62:65]
	v_mfma_f32_16x16x32_bf16 v[58:61], v[122:125], v[162:165], v[58:61]
	v_mfma_f32_16x16x32_bf16 v[46:49], v[98:101], v[170:173], v[46:49]
	v_mfma_f32_16x16x32_bf16 v[42:45], v[122:125], v[170:173], v[42:45]
	v_mfma_f32_16x16x32_bf16 v[30:33], v[98:101], v[178:181], v[30:33]
	v_mfma_f32_16x16x32_bf16 v[26:29], v[122:125], v[178:181], v[26:29]
	v_mfma_f32_16x16x32_bf16 v[14:17], v[98:101], v[186:189], v[14:17]
	v_mfma_f32_16x16x32_bf16 v[10:13], v[122:125], v[186:189], v[10:13]
	v_mfma_f32_16x16x32_bf16 v[62:65], v[110:113], v[166:169], v[62:65]
	v_mfma_f32_16x16x32_bf16 v[58:61], v[134:137], v[166:169], v[58:61]
	v_mfma_f32_16x16x32_bf16 v[46:49], v[110:113], v[174:177], v[46:49]
	v_mfma_f32_16x16x32_bf16 v[42:45], v[134:137], v[174:177], v[42:45]
	v_mfma_f32_16x16x32_bf16 v[30:33], v[110:113], v[182:185], v[30:33]
	v_mfma_f32_16x16x32_bf16 v[26:29], v[134:137], v[182:185], v[26:29]
	v_mfma_f32_16x16x32_bf16 v[14:17], v[110:113], v[204:207], v[14:17]
	v_mfma_f32_16x16x32_bf16 v[10:13], v[134:137], v[204:207], v[10:13]
	s_setprio 0
	s_setprio 1
	v_mfma_f32_16x16x32_bf16 v[54:57], v[138:141], v[162:165], v[54:57]
	v_mfma_f32_16x16x32_bf16 v[50:53], v[146:149], v[162:165], v[50:53]
	v_mfma_f32_16x16x32_bf16 v[38:41], v[138:141], v[170:173], v[38:41]
	v_mfma_f32_16x16x32_bf16 v[34:37], v[146:149], v[170:173], v[34:37]
	v_mfma_f32_16x16x32_bf16 v[22:25], v[138:141], v[178:181], v[22:25]
	v_mfma_f32_16x16x32_bf16 v[18:21], v[146:149], v[178:181], v[18:21]
	v_mfma_f32_16x16x32_bf16 v[6:9], v[138:141], v[186:189], v[6:9]
	v_mfma_f32_16x16x32_bf16 v[2:5], v[146:149], v[186:189], v[2:5]
	v_mfma_f32_16x16x32_bf16 v[54:57], v[142:145], v[166:169], v[54:57]
	v_mfma_f32_16x16x32_bf16 v[50:53], v[150:153], v[166:169], v[50:53]
	v_mfma_f32_16x16x32_bf16 v[38:41], v[142:145], v[174:177], v[38:41]
	v_mfma_f32_16x16x32_bf16 v[34:37], v[150:153], v[174:177], v[34:37]
	v_mfma_f32_16x16x32_bf16 v[22:25], v[142:145], v[182:185], v[22:25]
	v_mfma_f32_16x16x32_bf16 v[18:21], v[150:153], v[182:185], v[18:21]
	v_mfma_f32_16x16x32_bf16 v[6:9], v[142:145], v[204:207], v[6:9]
	v_mfma_f32_16x16x32_bf16 v[2:5], v[150:153], v[204:207], v[2:5]
	s_setprio 0
	s_barrier
	s_add_i32 s63, 0, 0x18000
	s_add_i32 s64, 0, 0x1c000
	v_add_u32_e32 v134, s63, v237
	v_add_u32_e32 v150, s64, v237
	ds_read_b128 v[98:101], v134
	ds_read_b128 v[110:113], v134 offset:1024
	ds_read_b128 v[122:125], v134 offset:2048
	ds_read_b128 v[134:137], v134 offset:3072
	ds_read_b128 v[138:141], v150
	ds_read_b128 v[142:145], v150 offset:1024
	ds_read_b128 v[146:149], v150 offset:2048
	ds_read_b128 v[150:153], v150 offset:3072
	s_add_u32 s18, s42, 0x40000
	s_addc_u32 s19, s43, 0
	s_mov_b32 m0, s47
	v_lshl_add_u64 v[216:217], s[18:19], 0, v[190:191]
	ds_read_b128 v[162:165], v241 offset:32768
	ds_read_b128 v[166:169], v241 offset:33792
	ds_read_b128 v[170:173], v241 offset:34816
	ds_read_b128 v[174:177], v241 offset:35840
	ds_read_b128 v[178:181], v241 offset:36864
	ds_read_b128 v[182:185], v241 offset:37888
	ds_read_b128 v[186:189], v241 offset:38912
	ds_read_b128 v[204:207], v241 offset:39936
	global_load_lds_dwordx4 v[216:217], off
	v_lshl_add_u64 v[216:217], s[18:19], 0, v[194:195]
	s_mov_b32 m0, s48
	s_nop 0
	global_load_lds_dwordx4 v[216:217], off
	s_waitcnt vmcnt(8)
	s_waitcnt lgkmcnt(0)
	s_barrier
	s_setprio 1
	s_waitcnt lgkmcnt(0)
	v_mfma_f32_16x16x32_bf16 v[158:161], v[98:101], v[162:165], v[158:161]
	v_mfma_f32_16x16x32_bf16 v[154:157], v[122:125], v[162:165], v[154:157]
	v_mfma_f32_16x16x32_bf16 v[118:121], v[98:101], v[170:173], v[118:121]
	v_mfma_f32_16x16x32_bf16 v[114:117], v[122:125], v[170:173], v[114:117]
	v_mfma_f32_16x16x32_bf16 v[94:97], v[98:101], v[178:181], v[94:97]
	v_mfma_f32_16x16x32_bf16 v[90:93], v[122:125], v[178:181], v[90:93]
	v_mfma_f32_16x16x32_bf16 v[78:81], v[98:101], v[186:189], v[78:81]
	v_mfma_f32_16x16x32_bf16 v[74:77], v[122:125], v[186:189], v[74:77]
	v_mfma_f32_16x16x32_bf16 v[158:161], v[110:113], v[166:169], v[158:161]
	v_mfma_f32_16x16x32_bf16 v[154:157], v[134:137], v[166:169], v[154:157]
	v_mfma_f32_16x16x32_bf16 v[118:121], v[110:113], v[174:177], v[118:121]
	v_mfma_f32_16x16x32_bf16 v[114:117], v[134:137], v[174:177], v[114:117]
	v_mfma_f32_16x16x32_bf16 v[94:97], v[110:113], v[182:185], v[94:97]
	v_mfma_f32_16x16x32_bf16 v[90:93], v[134:137], v[182:185], v[90:93]
	v_mfma_f32_16x16x32_bf16 v[78:81], v[110:113], v[204:207], v[78:81]
	v_mfma_f32_16x16x32_bf16 v[74:77], v[134:137], v[204:207], v[74:77]
	s_setprio 0
	s_setprio 1
	v_mfma_f32_16x16x32_bf16 v[130:133], v[138:141], v[162:165], v[130:133]
	v_mfma_f32_16x16x32_bf16 v[126:129], v[146:149], v[162:165], v[126:129]
	v_mfma_f32_16x16x32_bf16 v[106:109], v[138:141], v[170:173], v[106:109]
	v_mfma_f32_16x16x32_bf16 v[102:105], v[146:149], v[170:173], v[102:105]
	v_mfma_f32_16x16x32_bf16 v[86:89], v[138:141], v[178:181], v[86:89]
	v_mfma_f32_16x16x32_bf16 v[82:85], v[146:149], v[178:181], v[82:85]
	v_mfma_f32_16x16x32_bf16 v[70:73], v[138:141], v[186:189], v[70:73]
	v_mfma_f32_16x16x32_bf16 v[66:69], v[146:149], v[186:189], v[66:69]
	v_mfma_f32_16x16x32_bf16 v[130:133], v[142:145], v[166:169], v[130:133]
	v_mfma_f32_16x16x32_bf16 v[126:129], v[150:153], v[166:169], v[126:129]
	v_mfma_f32_16x16x32_bf16 v[106:109], v[142:145], v[174:177], v[106:109]
	v_mfma_f32_16x16x32_bf16 v[102:105], v[150:153], v[174:177], v[102:105]
	v_mfma_f32_16x16x32_bf16 v[86:89], v[142:145], v[182:185], v[86:89]
	v_mfma_f32_16x16x32_bf16 v[82:85], v[150:153], v[182:185], v[82:85]
	v_mfma_f32_16x16x32_bf16 v[70:73], v[142:145], v[204:207], v[70:73]
	v_mfma_f32_16x16x32_bf16 v[66:69], v[150:153], v[204:207], v[66:69]
	s_setprio 0
	s_barrier
; #define PG8_STAGE(bufoff, gbase, voff) do { _Pragma("unroll") for (int _i = 0; _i < 2; ++_i) \
;         __builtin_amdgcn_global_load_lds((const unsigned*)((const char*)(gbase) + (voff)[_i]), (PG8_LAS unsigned*)(lds + (bufoff) + ldsw + _i * 8192), 16, 0, 0); } while (0)
; #define PG8_LDA(dst, b, h) do { _Pragma("unroll") for (int m = 0; m < 4; ++m) _Pragma("unroll") for (int k = 0; k < 2; ++k) dst[m][k] = *(const PG8_LAS bf16x8*)(lds + PG8_SA(b, h) + aoff + m * 2048 + k * 1024); } while (0)
; #define PG8_MMA(ai, bj, At, Bt) do { __builtin_amdgcn_s_setprio(1); _Pragma("unroll") for (int m = 0; m < 4; ++m) _Pragma("unroll") for (int n = 0; n < 2; ++n) _Pragma("unroll") for (int k = 0; k < 2; ++k) \
;         acc[ai][bj][m][n] = __builtin_amdgcn_mfma_f32_16x16x32_bf16(Bt[n][k], At[m][k], acc[ai][bj][m][n], 0, 0, 0); __builtin_amdgcn_s_setprio(0); } while (0)
; #define PG8_WAIT_V(n) asm volatile("s_waitcnt vmcnt(" #n ")" ::: "memory")
; #define PG8_WAIT_L(n) asm volatile("s_waitcnt lgkmcnt(" #n ")" ::: "memory")
; #define PG8_BAR __builtin_amdgcn_s_barrier()
; #define PG8_SCHED __builtin_amdgcn_sched_barrier(0)
;     __device__ __forceinline__ void operator()(const f32x4 (&acc)[2][2][4][2], const Unit& u, int wr, int wc, int fr, int fq) const {
;     ...
;                 for (int bj = 0; bj < 2; ++bj) bva[ai][m][bj] = *(const u32x4*)(Xb + (size_t)(row0 + ai * HALF + m * 16) * DM + col0 + bj * HALF);
; template <class Epi, class Sched, bool ALIGN_EPI = false, bool SP2 = false>
; __device__ __forceinline__ void gemm_phase(PG8_LAS unsigned char* lds, const Gemm g, const Sched& S, const Epi& E) {
;     ...
;             const bool last = (t == nt - 2);
;             const char* a1 = cA + (size_t)(t + 1) * kstep;
;             const char* a2 = last ? nA : cA + (size_t)(t + 2) * kstep; const char* b2 = last ? nB : cB + (size_t)(t + 2) * kstep;
;             const char* a3 = a2 + kstep; const char* b3 = b2 + kstep;
;     ...
;             PG8_WAIT_V(8); PG8_WAIT_L(0); PG8_BAR; PG8_MMA(0, 0, At, B0); PG8_MMA(0, 1, At, B1); PG8_BAR; PG8_SCHED;
;             PG8_LDA(At, 1, 1); PG8_STAGE(PG8_SB(1, 0), b3, voffB); PG8_STAGE(PG8_SB(1, 1), b3 + hstep, voffB); PG8_STAGE(PG8_SA(1, 0), a3, voffA);
;             PG8_WAIT_V(8); PG8_WAIT_L(0); PG8_BAR; PG8_MMA(1, 0, At, B0); PG8_MMA(1, 1, At, B1); PG8_BAR; PG8_SCHED;
	s_add_i32 s18, s63, s44
	v_lshl_add_u64 v[208:209], v[208:209], 0, s[12:13]
	s_mov_b32 m0, s18
	ds_read_b128 v[162:165], v241 offset:49152
	ds_read_b128 v[166:169], v241 offset:50176
	ds_read_b128 v[170:173], v241 offset:51200
	ds_read_b128 v[174:177], v241 offset:52224
	ds_read_b128 v[178:181], v241 offset:53248
	ds_read_b128 v[182:185], v241 offset:54272
	ds_read_b128 v[186:189], v241 offset:55296
	ds_read_b128 v[204:207], v241 offset:56320
	global_load_lds_dwordx4 v[208:209], off
	s_add_i32 m0, s18, 0x2000
	s_add_u32 s18, s30, 0x40080
	v_lshl_add_u64 v[208:209], v[210:211], 0, s[12:13]
	s_addc_u32 s19, s31, 0
	s_add_i32 s30, s64, s44
	global_load_lds_dwordx4 v[208:209], off
	v_lshl_add_u64 v[208:209], s[18:19], 0, v[192:193]
	s_mov_b32 m0, s30
	s_nop 0
	global_load_lds_dwordx4 v[208:209], off
	v_lshl_add_u64 v[208:209], s[18:19], 0, v[196:197]
	s_add_i32 m0, s30, 0x2000
	s_nop 0
	global_load_lds_dwordx4 v[208:209], off
	v_lshl_add_u64 v[208:209], v[212:213], 0, s[12:13]
	s_mov_b32 m0, s52
	s_nop 0
	global_load_lds_dwordx4 v[208:209], off
	v_lshl_add_u64 v[208:209], v[214:215], 0, s[12:13]
	s_mov_b32 m0, s53
	s_nop 0
	global_load_lds_dwordx4 v[208:209], off
	s_waitcnt vmcnt(8)
	s_waitcnt lgkmcnt(0)
	s_barrier
	s_setprio 1
	s_waitcnt lgkmcnt(0)
	v_mfma_f32_16x16x32_bf16 v[62:65], v[98:101], v[162:165], v[62:65]
	v_mfma_f32_16x16x32_bf16 v[58:61], v[122:125], v[162:165], v[58:61]
	v_mfma_f32_16x16x32_bf16 v[46:49], v[98:101], v[170:173], v[46:49]
	v_mfma_f32_16x16x32_bf16 v[42:45], v[122:125], v[170:173], v[42:45]
	v_mfma_f32_16x16x32_bf16 v[30:33], v[98:101], v[178:181], v[30:33]
	v_mfma_f32_16x16x32_bf16 v[26:29], v[122:125], v[178:181], v[26:29]
	v_mfma_f32_16x16x32_bf16 v[14:17], v[98:101], v[186:189], v[14:17]
	v_mfma_f32_16x16x32_bf16 v[10:13], v[122:125], v[186:189], v[10:13]
	v_mfma_f32_16x16x32_bf16 v[62:65], v[110:113], v[166:169], v[62:65]
	v_mfma_f32_16x16x32_bf16 v[58:61], v[134:137], v[166:169], v[58:61]
	v_mfma_f32_16x16x32_bf16 v[46:49], v[110:113], v[174:177], v[46:49]
	v_mfma_f32_16x16x32_bf16 v[42:45], v[134:137], v[174:177], v[42:45]
	v_mfma_f32_16x16x32_bf16 v[30:33], v[110:113], v[182:185], v[30:33]
	v_mfma_f32_16x16x32_bf16 v[26:29], v[134:137], v[182:185], v[26:29]
	v_mfma_f32_16x16x32_bf16 v[14:17], v[110:113], v[204:207], v[14:17]
	v_mfma_f32_16x16x32_bf16 v[10:13], v[134:137], v[204:207], v[10:13]
	s_setprio 0
	s_setprio 1
	v_mfma_f32_16x16x32_bf16 v[54:57], v[138:141], v[162:165], v[54:57]
	v_mfma_f32_16x16x32_bf16 v[50:53], v[146:149], v[162:165], v[50:53]
	v_mfma_f32_16x16x32_bf16 v[38:41], v[138:141], v[170:173], v[38:41]
	v_mfma_f32_16x16x32_bf16 v[34:37], v[146:149], v[170:173], v[34:37]
	v_mfma_f32_16x16x32_bf16 v[22:25], v[138:141], v[178:181], v[22:25]
	v_mfma_f32_16x16x32_bf16 v[18:21], v[146:149], v[178:181], v[18:21]
	v_mfma_f32_16x16x32_bf16 v[6:9], v[138:141], v[186:189], v[6:9]
	v_mfma_f32_16x16x32_bf16 v[2:5], v[146:149], v[186:189], v[2:5]
	v_mfma_f32_16x16x32_bf16 v[54:57], v[142:145], v[166:169], v[54:57]
	v_mfma_f32_16x16x32_bf16 v[50:53], v[150:153], v[166:169], v[50:53]
	v_mfma_f32_16x16x32_bf16 v[38:41], v[142:145], v[174:177], v[38:41]
	v_mfma_f32_16x16x32_bf16 v[34:37], v[150:153], v[174:177], v[34:37]
	v_mfma_f32_16x16x32_bf16 v[22:25], v[142:145], v[182:185], v[22:25]
	v_mfma_f32_16x16x32_bf16 v[18:21], v[150:153], v[182:185], v[18:21]
	v_mfma_f32_16x16x32_bf16 v[6:9], v[142:145], v[204:207], v[6:9]
	v_mfma_f32_16x16x32_bf16 v[2:5], v[150:153], v[204:207], v[2:5]
	s_setprio 0
	s_barrier
	s_add_i32 s62, s62, 2
	s_add_u32 s40, s40, 0x100
	s_addc_u32 s41, s41, 0
	s_add_u32 s60, s60, 0x100
	s_addc_u32 s61, s61, 0
	s_cmp_gt_u32 s62, 13
	s_cbranch_scc1 .Lrp_gen_p3
	s_cmp_lg_u32 s62, 12
	s_cbranch_scc1 .LBB0_609
	s_cmpk_lg_i32 s33, 0x100
	s_cbranch_scc1 .LBB0_609
	ds_read_b128 v[98:101], v239
	ds_read_b128 v[110:113], v239 offset:1024
	ds_read_b128 v[122:125], v239 offset:2048
	ds_read_b128 v[134:137], v239 offset:3072
	ds_read_b128 v[138:141], v240
	ds_read_b128 v[142:145], v240 offset:1024
	ds_read_b128 v[146:149], v240 offset:2048
	ds_read_b128 v[150:153], v240 offset:3072
	s_add_u32 s18, s40, 0xfffc0080
	s_addc_u32 s19, s41, -1
	s_cmp_eq_u32 s62, 12
	s_cselect_b32 s43, s27, s19
	s_cselect_b32 s42, s39, s18
	s_cselect_b32 s31, s17, s61
	s_cselect_b32 s30, s59, s60
	v_lshl_add_u64 v[208:209], s[40:41], 0, v[198:199]
	s_add_i32 m0, s45, 0xc000
	ds_read_b128 v[162:165], v241
	ds_read_b128 v[166:169], v241 offset:1024
	ds_read_b128 v[170:173], v241 offset:2048
	ds_read_b128 v[174:177], v241 offset:3072
	ds_read_b128 v[178:181], v241 offset:4096
	ds_read_b128 v[182:185], v241 offset:5120
	ds_read_b128 v[186:189], v241 offset:6144
	ds_read_b128 v[204:207], v241 offset:7168
	global_load_lds_dwordx4 v[208:209], off
	v_lshl_add_u64 v[208:209], s[40:41], 0, v[200:201]
	s_add_i32 m0, s45, 0xe000
	s_nop 0
	global_load_lds_dwordx4 v[208:209], off
	v_lshl_or_b32 v255, s0, 8, v238
	v_lshl_add_u32 v235, s38, 8, v1
	v_lshlrev_b32_e32 v255, 1, v255
	v_lshl_add_u32 v255, v235, 11, v255
	s_mov_b64 s[84:85], s[20:21]
	global_load_dwordx4 v[242:245], v255, s[84:85]
	global_load_dwordx4 v[208:211], v255, s[84:85] offset:256
	s_add_u32 s84, s20, 0x8000
	s_addc_u32 s85, s21, 0
	global_load_dwordx4 v[212:215], v255, s[84:85]
	global_load_dwordx4 v[216:219], v255, s[84:85] offset:256
	s_add_u32 s84, s20, 0x10000
	s_addc_u32 s85, s21, 0
	global_load_dwordx4 v[220:223], v255, s[84:85]
	global_load_dwordx4 v[224:227], v255, s[84:85] offset:256
	s_add_u32 s84, s20, 0x18000
	s_addc_u32 s85, s21, 0
	global_load_dwordx4 v[228:231], v255, s[84:85]
	global_load_dwordx4 v[232:235], v255, s[84:85] offset:256
	s_add_u32 s84, s20, 0x40000
	s_addc_u32 s85, s21, 0
	global_load_dwordx4 v[246:249], v255, s[84:85]
	global_load_dwordx4 v[250:253], v255, s[84:85] offset:256
	s_waitcnt vmcnt(18)
	s_waitcnt lgkmcnt(0)
	s_barrier
; #define PG8_STAGE(bufoff, gbase, voff) do { _Pragma("unroll") for (int _i = 0; _i < 2; ++_i) \
;         __builtin_amdgcn_global_load_lds((const unsigned*)((const char*)(gbase) + (voff)[_i]), (PG8_LAS unsigned*)(lds + (bufoff) + ldsw + _i * 8192), 16, 0, 0); } while (0)
; #define PG8_LDA(dst, b, h) do { _Pragma("unroll") for (int m = 0; m < 4; ++m) _Pragma("unroll") for (int k = 0; k < 2; ++k) dst[m][k] = *(const PG8_LAS bf16x8*)(lds + PG8_SA(b, h) + aoff + m * 2048 + k * 1024); } while (0)
; #define PG8_LDB(dst, b, h) do { _Pragma("unroll") for (int n = 0; n < 2; ++n) _Pragma("unroll") for (int k = 0; k < 2; ++k) dst[n][k] = *(const PG8_LAS bf16x8*)(lds + PG8_SB(b, h) + boff + n * 2048 + k * 1024); } while (0)
; #define PG8_MMA(ai, bj, At, Bt) do { __builtin_amdgcn_s_setprio(1); _Pragma("unroll") for (int m = 0; m < 4; ++m) _Pragma("unroll") for (int n = 0; n < 2; ++n) _Pragma("unroll") for (int k = 0; k < 2; ++k) \
;         acc[ai][bj][m][n] = __builtin_amdgcn_mfma_f32_16x16x32_bf16(Bt[n][k], At[m][k], acc[ai][bj][m][n], 0, 0, 0); __builtin_amdgcn_s_setprio(0); } while (0)
; #define PG8_WAIT_V(n) asm volatile("s_waitcnt vmcnt(" #n ")" ::: "memory")
; #define PG8_WAIT_L(n) asm volatile("s_waitcnt lgkmcnt(" #n ")" ::: "memory")
; #define PG8_BAR __builtin_amdgcn_s_barrier()
; #define PG8_SCHED __builtin_amdgcn_sched_barrier(0)
; template <class Epi, class Sched, bool ALIGN_EPI = false, bool SP2 = false>
; __device__ __forceinline__ void gemm_phase(PG8_LAS unsigned char* lds, const Gemm g, const Sched& S, const Epi& E) {
;     ...
;             PG8_LDB(B0, 0, 0); PG8_LDB(B1, 0, 1); PG8_SCHED; PG8_LDA(At, 0, 0); PG8_STAGE(PG8_SA(1, 1), a1 + hstep, voffA);
;             PG8_WAIT_V(8); PG8_WAIT_L(0); PG8_BAR; PG8_MMA(0, 0, At, B0); PG8_MMA(0, 1, At, B1); PG8_BAR; PG8_SCHED;
;             PG8_LDA(At, 0, 1); PG8_STAGE(PG8_SB(0, 0), b2, voffB); PG8_STAGE(PG8_SB(0, 1), b2 + hstep, voffB); PG8_STAGE(PG8_SA(0, 0), a2, voffA);
;             PG8_WAIT_V(8); PG8_WAIT_L(0); PG8_BAR; PG8_MMA(1, 0, At, B0); PG8_MMA(1, 1, At, B1); PG8_BAR; PG8_SCHED;
;             PG8_LDB(B0, 1, 0); PG8_LDB(B1, 1, 1); PG8_SCHED; PG8_LDA(At, 1, 0); PG8_STAGE(PG8_SA(0, 1), a2 + hstep, voffA);
;             PG8_WAIT_V(8); PG8_WAIT_L(0); PG8_BAR; PG8_MMA(0, 0, At, B0); PG8_MMA(0, 1, At, B1); PG8_BAR; PG8_SCHED;
	s_setprio 1
	s_waitcnt lgkmcnt(0)
	v_mfma_f32_16x16x32_bf16 v[158:161], v[98:101], v[162:165], v[158:161]
	v_mfma_f32_16x16x32_bf16 v[154:157], v[122:125], v[162:165], v[154:157]
	v_mfma_f32_16x16x32_bf16 v[118:121], v[98:101], v[170:173], v[118:121]
	v_mfma_f32_16x16x32_bf16 v[114:117], v[122:125], v[170:173], v[114:117]
	v_mfma_f32_16x16x32_bf16 v[94:97], v[98:101], v[178:181], v[94:97]
	v_mfma_f32_16x16x32_bf16 v[90:93], v[122:125], v[178:181], v[90:93]
	v_mfma_f32_16x16x32_bf16 v[78:81], v[98:101], v[186:189], v[78:81]
	v_mfma_f32_16x16x32_bf16 v[74:77], v[122:125], v[186:189], v[74:77]
	v_mfma_f32_16x16x32_bf16 v[158:161], v[110:113], v[166:169], v[158:161]
	v_mfma_f32_16x16x32_bf16 v[154:157], v[134:137], v[166:169], v[154:157]
	v_mfma_f32_16x16x32_bf16 v[118:121], v[110:113], v[174:177], v[118:121]
	v_mfma_f32_16x16x32_bf16 v[114:117], v[134:137], v[174:177], v[114:117]
	v_mfma_f32_16x16x32_bf16 v[94:97], v[110:113], v[182:185], v[94:97]
	v_mfma_f32_16x16x32_bf16 v[90:93], v[134:137], v[182:185], v[90:93]
	v_mfma_f32_16x16x32_bf16 v[78:81], v[110:113], v[204:207], v[78:81]
	v_mfma_f32_16x16x32_bf16 v[74:77], v[134:137], v[204:207], v[74:77]
	s_setprio 0
	s_setprio 1
	v_mfma_f32_16x16x32_bf16 v[130:133], v[138:141], v[162:165], v[130:133]
	v_mfma_f32_16x16x32_bf16 v[126:129], v[146:149], v[162:165], v[126:129]
	v_mfma_f32_16x16x32_bf16 v[106:109], v[138:141], v[170:173], v[106:109]
	v_mfma_f32_16x16x32_bf16 v[102:105], v[146:149], v[170:173], v[102:105]
	v_mfma_f32_16x16x32_bf16 v[86:89], v[138:141], v[178:181], v[86:89]
	v_mfma_f32_16x16x32_bf16 v[82:85], v[146:149], v[178:181], v[82:85]
	v_mfma_f32_16x16x32_bf16 v[70:73], v[138:141], v[186:189], v[70:73]
	v_mfma_f32_16x16x32_bf16 v[66:69], v[146:149], v[186:189], v[66:69]
	v_mfma_f32_16x16x32_bf16 v[130:133], v[142:145], v[166:169], v[130:133]
	v_mfma_f32_16x16x32_bf16 v[126:129], v[150:153], v[166:169], v[126:129]
	v_mfma_f32_16x16x32_bf16 v[106:109], v[142:145], v[174:177], v[106:109]
	v_mfma_f32_16x16x32_bf16 v[102:105], v[150:153], v[174:177], v[102:105]
	v_mfma_f32_16x16x32_bf16 v[86:89], v[142:145], v[182:185], v[86:89]
	v_mfma_f32_16x16x32_bf16 v[82:85], v[150:153], v[182:185], v[82:85]
	v_mfma_f32_16x16x32_bf16 v[70:73], v[142:145], v[204:207], v[70:73]
	v_mfma_f32_16x16x32_bf16 v[66:69], v[150:153], v[204:207], v[66:69]
	s_setprio 0
	s_barrier
	s_add_i32 s18, s56, s44
	s_mov_b32 m0, s18
	ds_read_b128 v[162:165], v241 offset:16384
	ds_read_b128 v[166:169], v241 offset:17408
	ds_read_b128 v[170:173], v241 offset:18432
	ds_read_b128 v[174:177], v241 offset:19456
	ds_read_b128 v[178:181], v241 offset:20480
	ds_read_b128 v[182:185], v241 offset:21504
	ds_read_b128 v[186:189], v241 offset:22528
	ds_read_b128 v[204:207], v241 offset:23552
	s_add_i32 m0, s18, 0x2000
	s_add_u32 s18, s30, 0x40000
	s_addc_u32 s19, s31, 0
	s_add_i32 s63, s57, s44
	s_mov_b32 m0, s63
	s_add_i32 m0, s63, 0x2000
	s_nop 0
	s_mov_b32 m0, s45
	s_nop 0
	s_mov_b32 m0, s46
	s_nop 0
	s_waitcnt vmcnt(12)
	s_waitcnt lgkmcnt(0)
	s_barrier
	s_setprio 1
	s_waitcnt lgkmcnt(0)
	v_mfma_f32_16x16x32_bf16 v[62:65], v[98:101], v[162:165], v[62:65]
	v_mfma_f32_16x16x32_bf16 v[58:61], v[122:125], v[162:165], v[58:61]
	v_mfma_f32_16x16x32_bf16 v[46:49], v[98:101], v[170:173], v[46:49]
	v_mfma_f32_16x16x32_bf16 v[42:45], v[122:125], v[170:173], v[42:45]
	v_mfma_f32_16x16x32_bf16 v[30:33], v[98:101], v[178:181], v[30:33]
	v_mfma_f32_16x16x32_bf16 v[26:29], v[122:125], v[178:181], v[26:29]
	v_mfma_f32_16x16x32_bf16 v[14:17], v[98:101], v[186:189], v[14:17]
	v_mfma_f32_16x16x32_bf16 v[10:13], v[122:125], v[186:189], v[10:13]
	v_mfma_f32_16x16x32_bf16 v[62:65], v[110:113], v[166:169], v[62:65]
	v_mfma_f32_16x16x32_bf16 v[58:61], v[134:137], v[166:169], v[58:61]
	v_mfma_f32_16x16x32_bf16 v[46:49], v[110:113], v[174:177], v[46:49]
	v_mfma_f32_16x16x32_bf16 v[42:45], v[134:137], v[174:177], v[42:45]
	v_mfma_f32_16x16x32_bf16 v[30:33], v[110:113], v[182:185], v[30:33]
	v_mfma_f32_16x16x32_bf16 v[26:29], v[134:137], v[182:185], v[26:29]
	v_mfma_f32_16x16x32_bf16 v[14:17], v[110:113], v[204:207], v[14:17]
	v_mfma_f32_16x16x32_bf16 v[10:13], v[134:137], v[204:207], v[10:13]
	s_setprio 0
	s_setprio 1
	v_mfma_f32_16x16x32_bf16 v[54:57], v[138:141], v[162:165], v[54:57]
	v_mfma_f32_16x16x32_bf16 v[50:53], v[146:149], v[162:165], v[50:53]
	v_mfma_f32_16x16x32_bf16 v[38:41], v[138:141], v[170:173], v[38:41]
	v_mfma_f32_16x16x32_bf16 v[34:37], v[146:149], v[170:173], v[34:37]
	v_mfma_f32_16x16x32_bf16 v[22:25], v[138:141], v[178:181], v[22:25]
	v_mfma_f32_16x16x32_bf16 v[18:21], v[146:149], v[178:181], v[18:21]
	v_mfma_f32_16x16x32_bf16 v[6:9], v[138:141], v[186:189], v[6:9]
	v_mfma_f32_16x16x32_bf16 v[2:5], v[146:149], v[186:189], v[2:5]
	v_mfma_f32_16x16x32_bf16 v[54:57], v[142:145], v[166:169], v[54:57]
	v_mfma_f32_16x16x32_bf16 v[50:53], v[150:153], v[166:169], v[50:53]
	v_mfma_f32_16x16x32_bf16 v[38:41], v[142:145], v[174:177], v[38:41]
	v_mfma_f32_16x16x32_bf16 v[34:37], v[150:153], v[174:177], v[34:37]
	v_mfma_f32_16x16x32_bf16 v[22:25], v[142:145], v[182:185], v[22:25]
	v_mfma_f32_16x16x32_bf16 v[18:21], v[150:153], v[182:185], v[18:21]
	v_mfma_f32_16x16x32_bf16 v[6:9], v[142:145], v[204:207], v[6:9]
	v_mfma_f32_16x16x32_bf16 v[2:5], v[150:153], v[204:207], v[2:5]
	s_setprio 0
	s_barrier
; #define PG8_STAGE(bufoff, gbase, voff) do { _Pragma("unroll") for (int _i = 0; _i < 2; ++_i) \
;         __builtin_amdgcn_global_load_lds((const unsigned*)((const char*)(gbase) + (voff)[_i]), (PG8_LAS unsigned*)(lds + (bufoff) + ldsw + _i * 8192), 16, 0, 0); } while (0)
; #define PG8_LDA(dst, b, h) do { _Pragma("unroll") for (int m = 0; m < 4; ++m) _Pragma("unroll") for (int k = 0; k < 2; ++k) dst[m][k] = *(const PG8_LAS bf16x8*)(lds + PG8_SA(b, h) + aoff + m * 2048 + k * 1024); } while (0)
; #define PG8_LDB(dst, b, h) do { _Pragma("unroll") for (int n = 0; n < 2; ++n) _Pragma("unroll") for (int k = 0; k < 2; ++k) dst[n][k] = *(const PG8_LAS bf16x8*)(lds + PG8_SB(b, h) + boff + n * 2048 + k * 1024); } while (0)
; #define PG8_MMA(ai, bj, At, Bt) do { __builtin_amdgcn_s_setprio(1); _Pragma("unroll") for (int m = 0; m < 4; ++m) _Pragma("unroll") for (int n = 0; n < 2; ++n) _Pragma("unroll") for (int k = 0; k < 2; ++k) \
;         acc[ai][bj][m][n] = __builtin_amdgcn_mfma_f32_16x16x32_bf16(Bt[n][k], At[m][k], acc[ai][bj][m][n], 0, 0, 0); __builtin_amdgcn_s_setprio(0); } while (0)
; #define PG8_WAIT_V(n) asm volatile("s_waitcnt vmcnt(" #n ")" ::: "memory")
; #define PG8_WAIT_L(n) asm volatile("s_waitcnt lgkmcnt(" #n ")" ::: "memory")
; #define PG8_BAR __builtin_amdgcn_s_barrier()
; #define PG8_SCHED __builtin_amdgcn_sched_barrier(0)
; template <class Epi, class Sched, bool ALIGN_EPI = false, bool SP2 = false>
; __device__ __forceinline__ void gemm_phase(PG8_LAS unsigned char* lds, const Gemm g, const Sched& S, const Epi& E) {
;     ...
;             PG8_LDB(B0, 1, 0); PG8_LDB(B1, 1, 1); PG8_SCHED; PG8_LDA(At, 1, 0); PG8_STAGE(PG8_SA(0, 1), a2 + hstep, voffA);
;             PG8_WAIT_V(8); PG8_WAIT_L(0); PG8_BAR; PG8_MMA(0, 0, At, B0); PG8_MMA(0, 1, At, B1); PG8_BAR; PG8_SCHED;
;             PG8_LDA(At, 1, 1); PG8_STAGE(PG8_SB(1, 0), b3, voffB); PG8_STAGE(PG8_SB(1, 1), b3 + hstep, voffB); PG8_STAGE(PG8_SA(1, 0), a3, voffA);
;             PG8_WAIT_V(8); PG8_WAIT_L(0); PG8_BAR; PG8_MMA(1, 0, At, B0); PG8_MMA(1, 1, At, B1); PG8_BAR; PG8_SCHED;
	s_add_i32 s63, 0, 0x18000
	s_add_i32 s64, 0, 0x1c000
	v_add_u32_e32 v134, s63, v237
	v_add_u32_e32 v150, s64, v237
	ds_read_b128 v[98:101], v134
	ds_read_b128 v[110:113], v134 offset:1024
	ds_read_b128 v[122:125], v134 offset:2048
	ds_read_b128 v[134:137], v134 offset:3072
	ds_read_b128 v[138:141], v150
	ds_read_b128 v[142:145], v150 offset:1024
	ds_read_b128 v[146:149], v150 offset:2048
	ds_read_b128 v[150:153], v150 offset:3072
	s_add_u32 s18, s42, 0x40000
	s_addc_u32 s19, s43, 0
	s_mov_b32 m0, s47
	ds_read_b128 v[162:165], v241 offset:32768
	ds_read_b128 v[166:169], v241 offset:33792
	ds_read_b128 v[170:173], v241 offset:34816
	ds_read_b128 v[174:177], v241 offset:35840
	ds_read_b128 v[178:181], v241 offset:36864
	ds_read_b128 v[182:185], v241 offset:37888
	ds_read_b128 v[186:189], v241 offset:38912
	ds_read_b128 v[204:207], v241 offset:39936
	s_mov_b32 m0, s48
	s_nop 0
	s_waitcnt vmcnt(10)
	s_waitcnt lgkmcnt(0)
	s_barrier
	s_setprio 1
	s_waitcnt lgkmcnt(0)
	v_mfma_f32_16x16x32_bf16 v[158:161], v[98:101], v[162:165], v[158:161]
	v_mfma_f32_16x16x32_bf16 v[154:157], v[122:125], v[162:165], v[154:157]
	v_mfma_f32_16x16x32_bf16 v[118:121], v[98:101], v[170:173], v[118:121]
	v_mfma_f32_16x16x32_bf16 v[114:117], v[122:125], v[170:173], v[114:117]
	v_mfma_f32_16x16x32_bf16 v[94:97], v[98:101], v[178:181], v[94:97]
	v_mfma_f32_16x16x32_bf16 v[90:93], v[122:125], v[178:181], v[90:93]
	v_mfma_f32_16x16x32_bf16 v[78:81], v[98:101], v[186:189], v[78:81]
	v_mfma_f32_16x16x32_bf16 v[74:77], v[122:125], v[186:189], v[74:77]
	v_mfma_f32_16x16x32_bf16 v[158:161], v[110:113], v[166:169], v[158:161]
	v_mfma_f32_16x16x32_bf16 v[154:157], v[134:137], v[166:169], v[154:157]
	v_mfma_f32_16x16x32_bf16 v[118:121], v[110:113], v[174:177], v[118:121]
	v_mfma_f32_16x16x32_bf16 v[114:117], v[134:137], v[174:177], v[114:117]
	v_mfma_f32_16x16x32_bf16 v[94:97], v[110:113], v[182:185], v[94:97]
	v_mfma_f32_16x16x32_bf16 v[90:93], v[134:137], v[182:185], v[90:93]
	v_mfma_f32_16x16x32_bf16 v[78:81], v[110:113], v[204:207], v[78:81]
	v_mfma_f32_16x16x32_bf16 v[74:77], v[134:137], v[204:207], v[74:77]
	s_setprio 0
	s_setprio 1
	v_mfma_f32_16x16x32_bf16 v[130:133], v[138:141], v[162:165], v[130:133]
	v_mfma_f32_16x16x32_bf16 v[126:129], v[146:149], v[162:165], v[126:129]
	v_mfma_f32_16x16x32_bf16 v[106:109], v[138:141], v[170:173], v[106:109]
	v_mfma_f32_16x16x32_bf16 v[102:105], v[146:149], v[170:173], v[102:105]
	v_mfma_f32_16x16x32_bf16 v[86:89], v[138:141], v[178:181], v[86:89]
	v_mfma_f32_16x16x32_bf16 v[82:85], v[146:149], v[178:181], v[82:85]
	v_mfma_f32_16x16x32_bf16 v[70:73], v[138:141], v[186:189], v[70:73]
	v_mfma_f32_16x16x32_bf16 v[66:69], v[146:149], v[186:189], v[66:69]
	v_mfma_f32_16x16x32_bf16 v[130:133], v[142:145], v[166:169], v[130:133]
	v_mfma_f32_16x16x32_bf16 v[126:129], v[150:153], v[166:169], v[126:129]
	v_mfma_f32_16x16x32_bf16 v[106:109], v[142:145], v[174:177], v[106:109]
	v_mfma_f32_16x16x32_bf16 v[102:105], v[150:153], v[174:177], v[102:105]
	v_mfma_f32_16x16x32_bf16 v[86:89], v[142:145], v[182:185], v[86:89]
	v_mfma_f32_16x16x32_bf16 v[82:85], v[150:153], v[182:185], v[82:85]
	v_mfma_f32_16x16x32_bf16 v[70:73], v[142:145], v[204:207], v[70:73]
	v_mfma_f32_16x16x32_bf16 v[66:69], v[150:153], v[204:207], v[66:69]
	s_setprio 0
	s_barrier
	s_add_i32 s18, s63, s44
	s_mov_b32 m0, s18
	ds_read_b128 v[162:165], v241 offset:49152
	ds_read_b128 v[166:169], v241 offset:50176
	ds_read_b128 v[170:173], v241 offset:51200
	ds_read_b128 v[174:177], v241 offset:52224
	ds_read_b128 v[178:181], v241 offset:53248
	ds_read_b128 v[182:185], v241 offset:54272
	ds_read_b128 v[186:189], v241 offset:55296
	ds_read_b128 v[204:207], v241 offset:56320
	s_add_i32 m0, s18, 0x2000
	s_add_u32 s18, s30, 0x40080
	s_addc_u32 s19, s31, 0
	s_add_i32 s30, s64, s44
	s_mov_b32 m0, s30
	s_nop 0
	s_add_i32 m0, s30, 0x2000
	s_nop 0
	s_mov_b32 m0, s52
	s_nop 0
	s_mov_b32 m0, s53
	s_nop 0
	s_waitcnt vmcnt(10)
	s_waitcnt lgkmcnt(0)
	s_barrier
	s_setprio 1
	s_waitcnt lgkmcnt(0)
	v_mfma_f32_16x16x32_bf16 v[62:65], v[98:101], v[162:165], v[62:65]
	v_mfma_f32_16x16x32_bf16 v[58:61], v[122:125], v[162:165], v[58:61]
	v_mfma_f32_16x16x32_bf16 v[46:49], v[98:101], v[170:173], v[46:49]
	v_mfma_f32_16x16x32_bf16 v[42:45], v[122:125], v[170:173], v[42:45]
	v_mfma_f32_16x16x32_bf16 v[30:33], v[98:101], v[178:181], v[30:33]
	v_mfma_f32_16x16x32_bf16 v[26:29], v[122:125], v[178:181], v[26:29]
	v_mfma_f32_16x16x32_bf16 v[14:17], v[98:101], v[186:189], v[14:17]
	v_mfma_f32_16x16x32_bf16 v[10:13], v[122:125], v[186:189], v[10:13]
	v_mfma_f32_16x16x32_bf16 v[62:65], v[110:113], v[166:169], v[62:65]
	v_mfma_f32_16x16x32_bf16 v[58:61], v[134:137], v[166:169], v[58:61]
	v_mfma_f32_16x16x32_bf16 v[46:49], v[110:113], v[174:177], v[46:49]
	v_mfma_f32_16x16x32_bf16 v[42:45], v[134:137], v[174:177], v[42:45]
	v_mfma_f32_16x16x32_bf16 v[30:33], v[110:113], v[182:185], v[30:33]
	v_mfma_f32_16x16x32_bf16 v[26:29], v[134:137], v[182:185], v[26:29]
	v_mfma_f32_16x16x32_bf16 v[14:17], v[110:113], v[204:207], v[14:17]
	v_mfma_f32_16x16x32_bf16 v[10:13], v[134:137], v[204:207], v[10:13]
	s_setprio 0
	s_setprio 1
	v_mfma_f32_16x16x32_bf16 v[54:57], v[138:141], v[162:165], v[54:57]
	v_mfma_f32_16x16x32_bf16 v[50:53], v[146:149], v[162:165], v[50:53]
	v_mfma_f32_16x16x32_bf16 v[38:41], v[138:141], v[170:173], v[38:41]
	v_mfma_f32_16x16x32_bf16 v[34:37], v[146:149], v[170:173], v[34:37]
	v_mfma_f32_16x16x32_bf16 v[22:25], v[138:141], v[178:181], v[22:25]
	v_mfma_f32_16x16x32_bf16 v[18:21], v[146:149], v[178:181], v[18:21]
	v_mfma_f32_16x16x32_bf16 v[6:9], v[138:141], v[186:189], v[6:9]
	v_mfma_f32_16x16x32_bf16 v[2:5], v[146:149], v[186:189], v[2:5]
	v_mfma_f32_16x16x32_bf16 v[54:57], v[142:145], v[166:169], v[54:57]
	v_mfma_f32_16x16x32_bf16 v[50:53], v[150:153], v[166:169], v[50:53]
	v_mfma_f32_16x16x32_bf16 v[38:41], v[142:145], v[174:177], v[38:41]
	v_mfma_f32_16x16x32_bf16 v[34:37], v[150:153], v[174:177], v[34:37]
	v_mfma_f32_16x16x32_bf16 v[22:25], v[142:145], v[182:185], v[22:25]
	v_mfma_f32_16x16x32_bf16 v[18:21], v[150:153], v[182:185], v[18:21]
	v_mfma_f32_16x16x32_bf16 v[6:9], v[142:145], v[204:207], v[6:9]
	v_mfma_f32_16x16x32_bf16 v[2:5], v[150:153], v[204:207], v[2:5]
	s_setprio 0
	s_barrier
	s_add_i32 s62, s62, 2
	s_add_u32 s40, s40, 0x100
	s_addc_u32 s41, s41, 0
	s_add_u32 s60, s60, 0x100
	s_addc_u32 s61, s61, 0
	s_branch .Lrp_done_p3
; __device__ __forceinline__ u32x4 pack8(const f32x4 a, const f32x4 b) { u32x4 w; w.x = cvt_pk_bf16(a[0], a[1]); w.y = cvt_pk_bf16(a[2], a[3]); w.z = cvt_pk_bf16(b[0], b[1]); w.w = cvt_pk_bf16(b[2], b[3]); return w; }
;     __device__ __forceinline__ void operator()(const f32x4 (&acc)[2][2][4][2], const Unit& u, int wr, int wc, int fr, int fq) const {
;     ...
;         u32x4 bva[2][4][2];
; #pragma unroll
;         for (int ai = 0; ai < 2; ++ai)
; #pragma unroll
;             for (int m = 0; m < 4; ++m)
; #pragma unroll
;                 for (int bj = 0; bj < 2; ++bj) bva[ai][m][bj] = *(const u32x4*)(Xb + (size_t)(row0 + ai * HALF + m * 16) * DM + col0 + bj * HALF);
;         asm volatile("" :: "v"(bva[0][0][0]), "v"(bva[0][1][0]), "v"(bva[0][2][0]), "v"(bva[0][3][0]), "v"(bva[1][0][0]), "v"(bva[1][1][0]), "v"(bva[1][2][0]), "v"(bva[1][3][0]), "v"(bva[0][0][1]), "v"(bva[0][1][1]), "v"(bva[0][2][1]), "v"(bva[0][3][1]), "v"(bva[1][0][1]), "v"(bva[1][1][1]), "v"(bva[1][2][1]), "v"(bva[1][3][1]));
; #pragma unroll
;         for (int ai = 0; ai < 2; ++ai) {
; #pragma unroll
;             for (int m = 0; m < 4; ++m) { const int row = row0 + ai * HALF + m * 16; float ss = 0.f;
; #pragma unroll
;                 for (int bj = 0; bj < 2; ++bj) { const size_t off = (size_t)row * DM + col0 + bj * HALF; const u32x4 b = bva[ai][m][bj];
;                     f32x4 x0 = (f32x4){__builtin_bit_cast(float, b.x << 16), __builtin_bit_cast(float, b.x & 0xffff0000u), __builtin_bit_cast(float, b.y << 16), __builtin_bit_cast(float, b.y & 0xffff0000u)};
;                     f32x4 x1 = (f32x4){__builtin_bit_cast(float, b.z << 16), __builtin_bit_cast(float, b.z & 0xffff0000u), __builtin_bit_cast(float, b.w << 16), __builtin_bit_cast(float, b.w & 0xffff0000u)};
;                     x0 += acc[ai][bj][m][0]; x1 += acc[ai][bj][m][1];
;                     ss += (x0[0] * x0[0] + x0[1] * x0[1]) + (x0[2] * x0[2] + x0[3] * x0[3]) + (x1[0] * x1[0] + x1[1] * x1[1]) + (x1[2] * x1[2] + x1[3] * x1[3]);
;                     *(u32x4*)(Xb + off) = pack8(x0, x1); }
;                 ss = sum_fq(ss);
;                 if (fq == 0) SS[(size_t)row * 16 + u.pn * 4 + wc] = ss; }
.Lrp_gen_p3:
	v_lshl_or_b32 v255, s0, 8, v238
	v_lshl_add_u32 v235, s38, 8, v1
	v_lshlrev_b32_e32 v255, 1, v255
	v_lshl_add_u32 v255, v235, 11, v255
	s_mov_b64 s[84:85], s[20:21]
	global_load_dwordx4 v[242:245], v255, s[84:85]
	global_load_dwordx4 v[208:211], v255, s[84:85] offset:256
	s_add_u32 s84, s20, 0x8000
	s_addc_u32 s85, s21, 0
	global_load_dwordx4 v[212:215], v255, s[84:85]
	global_load_dwordx4 v[216:219], v255, s[84:85] offset:256
	s_add_u32 s84, s20, 0x10000
	s_addc_u32 s85, s21, 0
	global_load_dwordx4 v[220:223], v255, s[84:85]
	global_load_dwordx4 v[224:227], v255, s[84:85] offset:256
	s_add_u32 s84, s20, 0x18000
	s_addc_u32 s85, s21, 0
	global_load_dwordx4 v[228:231], v255, s[84:85]
	global_load_dwordx4 v[232:235], v255, s[84:85] offset:256
	s_add_u32 s84, s20, 0x40000
	s_addc_u32 s85, s21, 0
	global_load_dwordx4 v[246:249], v255, s[84:85]
	global_load_dwordx4 v[250:253], v255, s[84:85] offset:256
.Lrp_done_p3:
	s_and_b64 vcc, exec, s[14:15]
	s_cbranch_vccz .LBB0_612
	s_barrier
.LBB0_612:
	s_waitcnt vmcnt(0)
	v_mov_b32_e32 v186, v208
	v_mov_b32_e32 v187, v209
	v_mov_b32_e32 v188, v210
	v_mov_b32_e32 v189, v211
	v_mov_b32_e32 v182, v212
	v_mov_b32_e32 v183, v213
	v_mov_b32_e32 v184, v214
	v_mov_b32_e32 v185, v215
	v_mov_b32_e32 v178, v216
	v_mov_b32_e32 v179, v217
	v_mov_b32_e32 v180, v218
	v_mov_b32_e32 v181, v219
	v_mov_b32_e32 v174, v220
	v_mov_b32_e32 v175, v221
	v_mov_b32_e32 v176, v222
	v_mov_b32_e32 v177, v223
	v_mov_b32_e32 v170, v224
	v_mov_b32_e32 v171, v225
	v_mov_b32_e32 v172, v226
	v_mov_b32_e32 v173, v227
	v_mov_b32_e32 v166, v228
	v_mov_b32_e32 v167, v229
	v_mov_b32_e32 v168, v230
	v_mov_b32_e32 v169, v231
	v_mov_b32_e32 v162, v232
	v_mov_b32_e32 v163, v233
	v_mov_b32_e32 v164, v234
	v_mov_b32_e32 v165, v235
	v_mov_b32_e32 v150, v246
	v_mov_b32_e32 v151, v247
	v_mov_b32_e32 v152, v248
	v_mov_b32_e32 v153, v249
	v_mov_b32_e32 v146, v250
	v_mov_b32_e32 v147, v251
	v_mov_b32_e32 v148, v252
	v_mov_b32_e32 v149, v253
	v_lshl_or_b32 v206, s0, 8, v238
	v_lshl_add_u32 v234, s38, 8, v1
	v_ashrrev_i32_e32 v207, 31, v206
	v_lshlrev_b64 v[246:247], 1, v[206:207]
	v_ashrrev_i32_e32 v235, 31, v234
	v_or_b32_e32 v230, 16, v234
	v_lshl_add_u64 v[98:99], s[20:21], 0, v[246:247]
	v_lshlrev_b64 v[248:249], 11, v[234:235]
	v_ashrrev_i32_e32 v231, 31, v230
	v_or_b32_e32 v226, 32, v234
	v_lshl_add_u64 v[100:101], v[98:99], 0, v[248:249]
	v_lshlrev_b64 v[232:233], 11, v[230:231]
	v_ashrrev_i32_e32 v227, 31, v226
	v_or_b32_e32 v222, 48, v234
	v_lshl_add_u64 v[100:101], v[98:99], 0, v[232:233]
	v_lshlrev_b64 v[228:229], 11, v[226:227]
	v_ashrrev_i32_e32 v223, 31, v222
	v_add_u32_e32 v218, 0x80, v234
	v_lshl_add_u64 v[100:101], v[98:99], 0, v[228:229]
	v_lshlrev_b64 v[224:225], 11, v[222:223]
	v_ashrrev_i32_e32 v219, 31, v218
	v_add_u32_e32 v214, 0x90, v234
	v_lshl_add_u64 v[100:101], v[98:99], 0, v[224:225]
	v_lshlrev_b64 v[220:221], 11, v[218:219]
	v_ashrrev_i32_e32 v215, 31, v214
	v_add_u32_e32 v210, 0xa0, v234
	v_add_u32_e32 v204, 0xb0, v234
	v_lshl_add_u64 v[100:101], v[98:99], 0, v[220:221]
	v_lshlrev_b64 v[216:217], 11, v[214:215]
	v_ashrrev_i32_e32 v211, 31, v210
	v_ashrrev_i32_e32 v205, 31, v204
	v_lshl_add_u64 v[100:101], v[98:99], 0, v[216:217]
	v_lshlrev_b64 v[212:213], 11, v[210:211]
	v_lshlrev_b64 v[208:209], 11, v[204:205]
	global_load_dwordx4 v[142:145], v[100:101], off
	global_load_dwordx4 v[138:141], v[100:101], off offset:256
	v_lshl_add_u64 v[100:101], v[98:99], 0, v[212:213]
	v_lshl_add_u64 v[98:99], v[98:99], 0, v[208:209]
	global_load_dwordx4 v[134:137], v[100:101], off
	global_load_dwordx4 v[122:125], v[100:101], off offset:256
	global_load_dwordx4 v[110:113], v[98:99], off
	s_nop 0
	global_load_dwordx4 v[98:101], v[98:99], off offset:256
	s_lshl_b32 s38, s0, 2
	s_ashr_i32 s39, s38, 31
	v_lshlrev_b32_e32 v250, 16, v242
	v_and_b32_e32 v251, 0xffff0000, v242
	v_lshlrev_b32_e32 v242, 16, v243
	v_and_b32_e32 v243, 0xffff0000, v243
	v_lshlrev_b32_e32 v252, 16, v244
	v_and_b32_e32 v253, 0xffff0000, v244
	v_lshlrev_b32_e32 v244, 16, v245
	v_and_b32_e32 v245, 0xffff0000, v245
	v_pk_add_f32 v[160:161], v[160:161], v[242:243]
	v_pk_add_f32 v[158:159], v[158:159], v[250:251]
	v_pk_add_f32 v[242:243], v[156:157], v[244:245]
	v_pk_add_f32 v[156:157], v[154:155], v[252:253]
	v_mul_f32_e32 v154, v159, v159
	v_mul_f32_e32 v155, v161, v161
	v_fmac_f32_e32 v154, v158, v158
	v_fmac_f32_e32 v155, v160, v160
	v_add_f32_e32 v154, v154, v155
	v_mul_f32_e32 v155, v157, v157
	v_fmac_f32_e32 v155, v156, v156
	v_add_f32_e32 v154, v155, v154
	v_mul_f32_e32 v155, v243, v243
	v_fmac_f32_e32 v155, v242, v242
	v_add_f32_e32 v244, v155, v154
	v_cvt_pk_bf16_f32 v154, v158, v159
	v_lshl_add_u64 v[158:159], s[20:21], 0, v[248:249]
	v_cvt_pk_bf16_f32 v155, v160, v161
	v_cvt_pk_bf16_f32 v156, v156, v157
	v_cvt_pk_bf16_f32 v157, v242, v243
	v_lshl_add_u64 v[158:159], v[158:159], 0, v[246:247]
	global_store_dwordx4 v[158:159], v[154:157], off
	v_lshlrev_b32_e32 v160, 16, v188
	v_and_b32_e32 v161, 0xffff0000, v188
	v_lshlrev_b32_e32 v154, 16, v186
	v_and_b32_e32 v155, 0xffff0000, v186
	v_lshlrev_b32_e32 v156, 16, v187
	v_and_b32_e32 v157, 0xffff0000, v187
	v_lshlrev_b32_e32 v186, 16, v189
	v_and_b32_e32 v187, 0xffff0000, v189
	v_pk_add_f32 v[132:133], v[132:133], v[156:157]
	v_pk_add_f32 v[130:131], v[130:131], v[154:155]
	v_pk_add_f32 v[154:155], v[128:129], v[186:187]
	v_pk_add_f32 v[128:129], v[126:127], v[160:161]
	v_mul_f32_e32 v126, v131, v131
	v_mul_f32_e32 v127, v133, v133
	v_fmac_f32_e32 v126, v130, v130
	v_fmac_f32_e32 v127, v132, v132
	v_add_f32_e32 v126, v126, v127
	v_mul_f32_e32 v127, v129, v129
	v_fmac_f32_e32 v127, v128, v128
	v_add_f32_e32 v126, v127, v126
	v_mul_f32_e32 v127, v155, v155
	v_fmac_f32_e32 v127, v154, v154
	v_add_f32_e32 v126, v127, v126
	v_add_f32_e32 v156, v244, v126
	v_cvt_pk_bf16_f32 v126, v130, v131
	v_cvt_pk_bf16_f32 v127, v132, v133
	v_cvt_pk_bf16_f32 v128, v128, v129
	v_cvt_pk_bf16_f32 v129, v154, v155
	global_store_dwordx4 v[158:159], v[126:129], off offset:256
	s_nop 1
	v_mov_b32_e32 v126, v156
	s_nop 1
	v_permlane32_swap_b32_e32 v156, v126
	v_add_f32_e32 v126, v156, v126
	v_mov_b32_e32 v127, v126
	s_nop 1
	v_permlane16_swap_b32_e32 v126, v127
	s_and_saveexec_b64 s[30:31], s[2:3]
	s_cbranch_execz .LBB0_614
	v_add_f32_e32 v128, v126, v127
	v_lshlrev_b64 v[126:127], 6, v[234:235]
	v_lshl_add_u64 v[126:127], s[6:7], 0, v[126:127]
	v_lshl_add_u64 v[126:127], s[38:39], 2, v[126:127]
	s_lshl_b32 s0, s49, 2
	v_lshl_add_u64 v[126:127], v[126:127], 0, s[0:1]
	global_store_dword v[126:127], v128, off

; __device__ __forceinline__ u32x4 pack8(const f32x4 a, const f32x4 b) { u32x4 w; w.x = cvt_pk_bf16(a[0], a[1]); w.y = cvt_pk_bf16(a[2], a[3]); w.z = cvt_pk_bf16(b[0], b[1]); w.w = cvt_pk_bf16(b[2], b[3]); return w; }
;     __device__ __forceinline__ void operator()(const f32x4 (&acc)[2][2][4][2], const Unit& u, int wr, int wc, int fr, int fq) const {
;     ...
;             for (int m = 0; m < 4; ++m) { const int row = row0 + ai * HALF + m * 16; float ss = 0.f;
; #pragma unroll
;                 for (int bj = 0; bj < 2; ++bj) { const size_t off = (size_t)row * DM + col0 + bj * HALF; const u32x4 b = bva[ai][m][bj];
;                     f32x4 x0 = (f32x4){__builtin_bit_cast(float, b.x << 16), __builtin_bit_cast(float, b.x & 0xffff0000u), __builtin_bit_cast(float, b.y << 16), __builtin_bit_cast(float, b.y & 0xffff0000u)};
;                     f32x4 x1 = (f32x4){__builtin_bit_cast(float, b.z << 16), __builtin_bit_cast(float, b.z & 0xffff0000u), __builtin_bit_cast(float, b.w << 16), __builtin_bit_cast(float, b.w & 0xffff0000u)};
;                     x0 += acc[ai][bj][m][0]; x1 += acc[ai][bj][m][1];
;                     ss += (x0[0] * x0[0] + x0[1] * x0[1]) + (x0[2] * x0[2] + x0[3] * x0[3]) + (x1[0] * x1[0] + x1[1] * x1[1]) + (x1[2] * x1[2] + x1[3] * x1[3]);
;                     *(u32x4*)(Xb + off) = pack8(x0, x1); }
;                 ss = sum_fq(ss);
;                 if (fq == 0) SS[(size_t)row * 16 + u.pn * 4 + wc] = ss; }
.LBB0_622:
	s_or_b64 exec, exec, s[30:31]
	s_waitcnt vmcnt(10)
	v_lshlrev_b32_e32 v50, 16, v142
	v_and_b32_e32 v51, 0xffff0000, v142
	v_lshlrev_b32_e32 v52, 16, v143
	v_and_b32_e32 v53, 0xffff0000, v143
	v_lshlrev_b32_e32 v54, 16, v144
	v_and_b32_e32 v55, 0xffff0000, v144
	v_lshlrev_b32_e32 v56, 16, v145
	v_and_b32_e32 v57, 0xffff0000, v145
	v_pk_add_f32 v[48:49], v[48:49], v[52:53]
	v_pk_add_f32 v[46:47], v[46:47], v[50:51]
	v_pk_add_f32 v[50:51], v[44:45], v[56:57]
	v_pk_add_f32 v[44:45], v[42:43], v[54:55]
	v_mul_f32_e32 v42, v47, v47
	v_mul_f32_e32 v43, v49, v49
	v_fmac_f32_e32 v42, v46, v46
	v_fmac_f32_e32 v43, v48, v48
	v_add_f32_e32 v42, v42, v43
	v_mul_f32_e32 v43, v45, v45
	v_fmac_f32_e32 v43, v44, v44
	v_add_f32_e32 v42, v43, v42
	v_mul_f32_e32 v43, v51, v51
	v_fmac_f32_e32 v43, v50, v50
	v_add_f32_e32 v52, v43, v42
	v_cvt_pk_bf16_f32 v42, v46, v47
	v_lshl_add_u64 v[46:47], s[20:21], 0, v[216:217]
	v_cvt_pk_bf16_f32 v43, v48, v49
	v_cvt_pk_bf16_f32 v44, v44, v45
	v_cvt_pk_bf16_f32 v45, v50, v51
	v_lshl_add_u64 v[46:47], v[206:207], 1, v[46:47]
	global_store_dwordx4 v[46:47], v[42:45], off
	v_lshlrev_b32_e32 v48, 16, v140
	v_and_b32_e32 v49, 0xffff0000, v140
	v_lshlrev_b32_e32 v42, 16, v138
	v_and_b32_e32 v43, 0xffff0000, v138
	v_lshlrev_b32_e32 v44, 16, v139
	v_and_b32_e32 v45, 0xffff0000, v139
	v_lshlrev_b32_e32 v50, 16, v141
	v_and_b32_e32 v51, 0xffff0000, v141
	v_pk_add_f32 v[40:41], v[40:41], v[44:45]
	v_pk_add_f32 v[38:39], v[38:39], v[42:43]
	v_pk_add_f32 v[42:43], v[36:37], v[50:51]
	v_pk_add_f32 v[36:37], v[34:35], v[48:49]
	v_mul_f32_e32 v34, v39, v39
	v_mul_f32_e32 v35, v41, v41
	v_fmac_f32_e32 v34, v38, v38
	v_fmac_f32_e32 v35, v40, v40
	v_add_f32_e32 v34, v34, v35
	v_mul_f32_e32 v35, v37, v37
	v_fmac_f32_e32 v35, v36, v36
	v_add_f32_e32 v34, v35, v34
	v_mul_f32_e32 v35, v43, v43
	v_fmac_f32_e32 v35, v42, v42
	v_add_f32_e32 v34, v35, v34
	v_add_f32_e32 v44, v52, v34
	v_cvt_pk_bf16_f32 v34, v38, v39
	v_cvt_pk_bf16_f32 v35, v40, v41
	v_cvt_pk_bf16_f32 v36, v36, v37
	v_cvt_pk_bf16_f32 v37, v42, v43
	global_store_dwordx4 v[46:47], v[34:37], off offset:256
	s_nop 1
	v_mov_b32_e32 v34, v44
	s_nop 1
	v_permlane32_swap_b32_e32 v44, v34
	v_add_f32_e32 v34, v44, v34
	v_mov_b32_e32 v35, v34
	s_nop 1
	v_permlane16_swap_b32_e32 v34, v35
	s_and_saveexec_b64 s[30:31], s[2:3]
	s_cbranch_execz .LBB0_624
	v_add_f32_e32 v36, v34, v35
	v_lshlrev_b64 v[34:35], 6, v[214:215]
	v_lshl_add_u64 v[34:35], s[6:7], 0, v[34:35]
	v_lshl_add_u64 v[34:35], s[38:39], 2, v[34:35]
	s_lshl_b32 s0, s49, 2
	v_lshl_add_u64 v[34:35], v[34:35], 0, s[0:1]
	global_store_dword v[34:35], v36, off

; #define PG8_STAGE(bufoff, gbase, voff) do { _Pragma("unroll") for (int _i = 0; _i < 2; ++_i) \
;         __builtin_amdgcn_global_load_lds((const unsigned*)((const char*)(gbase) + (voff)[_i]), (PG8_LAS unsigned*)(lds + (bufoff) + ldsw + _i * 8192), 16, 0, 0); } while (0)
; #define PG8_LDA(dst, b, h) do { _Pragma("unroll") for (int m = 0; m < 4; ++m) _Pragma("unroll") for (int k = 0; k < 2; ++k) dst[m][k] = *(const PG8_LAS bf16x8*)(lds + PG8_SA(b, h) + aoff + m * 2048 + k * 1024); } while (0)
; #define PG8_LDB(dst, b, h) do { _Pragma("unroll") for (int n = 0; n < 2; ++n) _Pragma("unroll") for (int k = 0; k < 2; ++k) dst[n][k] = *(const PG8_LAS bf16x8*)(lds + PG8_SB(b, h) + boff + n * 2048 + k * 1024); } while (0)
; #define PG8_MMA(ai, bj, At, Bt) do { __builtin_amdgcn_s_setprio(1); _Pragma("unroll") for (int m = 0; m < 4; ++m) _Pragma("unroll") for (int n = 0; n < 2; ++n) _Pragma("unroll") for (int k = 0; k < 2; ++k) \
;         acc[ai][bj][m][n] = __builtin_amdgcn_mfma_f32_16x16x32_bf16(Bt[n][k], At[m][k], acc[ai][bj][m][n], 0, 0, 0); __builtin_amdgcn_s_setprio(0); } while (0)
; #define PG8_WAIT_V(n) asm volatile("s_waitcnt vmcnt(" #n ")" ::: "memory")
; #define PG8_WAIT_L(n) asm volatile("s_waitcnt lgkmcnt(" #n ")" ::: "memory")
; #define PG8_BAR __builtin_amdgcn_s_barrier()
; #define PG8_SCHED __builtin_amdgcn_sched_barrier(0)
; template <class Epi, class Sched, bool ALIGN_EPI = false, bool SP2 = false>
; __device__ __forceinline__ void gemm_phase(PG8_LAS unsigned char* lds, const Gemm g, const Sched& S, const Epi& E) {
;     ...
;             PG8_LDB(B0, 0, 0); PG8_LDB(B1, 0, 1); PG8_SCHED; PG8_LDA(At, 0, 0); PG8_STAGE(PG8_SA(1, 1), a1 + hstep, voffA);
;             PG8_WAIT_V(8); PG8_WAIT_L(0); PG8_BAR; PG8_MMA(0, 0, At, B0); PG8_MMA(0, 1, At, B1); PG8_BAR; PG8_SCHED;
;             PG8_LDA(At, 0, 1); PG8_STAGE(PG8_SB(0, 0), b2, voffB); PG8_STAGE(PG8_SB(0, 1), b2 + hstep, voffB); PG8_STAGE(PG8_SA(0, 0), a2, voffA);
;             PG8_WAIT_V(8); PG8_WAIT_L(0); PG8_BAR; PG8_MMA(1, 0, At, B0); PG8_MMA(1, 1, At, B1); PG8_BAR; PG8_SCHED;
.LBB0_892:
	ds_read_b128 v[98:101], v239
	ds_read_b128 v[110:113], v239 offset:1024
	ds_read_b128 v[122:125], v239 offset:2048
	ds_read_b128 v[134:137], v239 offset:3072
	ds_read_b128 v[138:141], v240
	ds_read_b128 v[142:145], v240 offset:1024
	ds_read_b128 v[146:149], v240 offset:2048
	ds_read_b128 v[150:153], v240 offset:3072
	s_add_u32 s18, s34, 0xfff50080
	s_addc_u32 s19, s35, -1
	s_cmp_eq_u32 s60, 40
	s_cselect_b32 s39, s1, s19
	s_cselect_b32 s38, s0, s18
	s_cselect_b32 s37, s31, s59
	s_cselect_b32 s36, s30, s58
	v_lshl_add_u64 v[208:209], s[34:35], 0, v[198:199]
	s_add_i32 m0, s41, 0xc000
	ds_read_b128 v[162:165], v241
	ds_read_b128 v[166:169], v241 offset:1024
	ds_read_b128 v[170:173], v241 offset:2048
	ds_read_b128 v[174:177], v241 offset:3072
	ds_read_b128 v[178:181], v241 offset:4096
	ds_read_b128 v[182:185], v241 offset:5120
	ds_read_b128 v[186:189], v241 offset:6144
	ds_read_b128 v[204:207], v241 offset:7168
	global_load_lds_dwordx4 v[208:209], off
	v_lshl_add_u64 v[208:209], s[34:35], 0, v[200:201]
	s_add_i32 m0, s41, 0xe000
	s_nop 0
	global_load_lds_dwordx4 v[208:209], off
	s_waitcnt vmcnt(8)
	s_waitcnt lgkmcnt(0)
	s_barrier
	s_setprio 1
	s_waitcnt lgkmcnt(0)
	v_mfma_f32_16x16x32_bf16 v[158:161], v[98:101], v[162:165], v[158:161]
	v_mfma_f32_16x16x32_bf16 v[154:157], v[122:125], v[162:165], v[154:157]
	v_mfma_f32_16x16x32_bf16 v[118:121], v[98:101], v[170:173], v[118:121]
	v_mfma_f32_16x16x32_bf16 v[114:117], v[122:125], v[170:173], v[114:117]
	v_mfma_f32_16x16x32_bf16 v[94:97], v[98:101], v[178:181], v[94:97]
	v_mfma_f32_16x16x32_bf16 v[90:93], v[122:125], v[178:181], v[90:93]
	v_mfma_f32_16x16x32_bf16 v[78:81], v[98:101], v[186:189], v[78:81]
	v_mfma_f32_16x16x32_bf16 v[74:77], v[122:125], v[186:189], v[74:77]
	v_mfma_f32_16x16x32_bf16 v[158:161], v[110:113], v[166:169], v[158:161]
	v_mfma_f32_16x16x32_bf16 v[154:157], v[134:137], v[166:169], v[154:157]
	v_mfma_f32_16x16x32_bf16 v[118:121], v[110:113], v[174:177], v[118:121]
	v_mfma_f32_16x16x32_bf16 v[114:117], v[134:137], v[174:177], v[114:117]
	v_mfma_f32_16x16x32_bf16 v[94:97], v[110:113], v[182:185], v[94:97]
	v_mfma_f32_16x16x32_bf16 v[90:93], v[134:137], v[182:185], v[90:93]
	v_mfma_f32_16x16x32_bf16 v[78:81], v[110:113], v[204:207], v[78:81]
	v_mfma_f32_16x16x32_bf16 v[74:77], v[134:137], v[204:207], v[74:77]
	s_setprio 0
	s_setprio 1
	v_mfma_f32_16x16x32_bf16 v[130:133], v[138:141], v[162:165], v[130:133]
	v_mfma_f32_16x16x32_bf16 v[126:129], v[146:149], v[162:165], v[126:129]
	v_mfma_f32_16x16x32_bf16 v[106:109], v[138:141], v[170:173], v[106:109]
	v_mfma_f32_16x16x32_bf16 v[102:105], v[146:149], v[170:173], v[102:105]
	v_mfma_f32_16x16x32_bf16 v[86:89], v[138:141], v[178:181], v[86:89]
	v_mfma_f32_16x16x32_bf16 v[82:85], v[146:149], v[178:181], v[82:85]
	v_mfma_f32_16x16x32_bf16 v[70:73], v[138:141], v[186:189], v[70:73]
	v_mfma_f32_16x16x32_bf16 v[66:69], v[146:149], v[186:189], v[66:69]
	v_mfma_f32_16x16x32_bf16 v[130:133], v[142:145], v[166:169], v[130:133]
	v_mfma_f32_16x16x32_bf16 v[126:129], v[150:153], v[166:169], v[126:129]
	v_mfma_f32_16x16x32_bf16 v[106:109], v[142:145], v[174:177], v[106:109]
	v_mfma_f32_16x16x32_bf16 v[102:105], v[150:153], v[174:177], v[102:105]
	v_mfma_f32_16x16x32_bf16 v[86:89], v[142:145], v[182:185], v[86:89]
	v_mfma_f32_16x16x32_bf16 v[82:85], v[150:153], v[182:185], v[82:85]
	v_mfma_f32_16x16x32_bf16 v[70:73], v[142:145], v[204:207], v[70:73]
	v_mfma_f32_16x16x32_bf16 v[66:69], v[150:153], v[204:207], v[66:69]
	s_setprio 0
	s_barrier
	s_add_i32 s18, s52, s40
	v_lshl_add_u64 v[208:209], s[36:37], 0, v[192:193]
	s_mov_b32 m0, s18
	ds_read_b128 v[162:165], v241 offset:16384
	ds_read_b128 v[166:169], v241 offset:17408
	ds_read_b128 v[170:173], v241 offset:18432
	ds_read_b128 v[174:177], v241 offset:19456
	ds_read_b128 v[178:181], v241 offset:20480
	ds_read_b128 v[182:185], v241 offset:21504
	ds_read_b128 v[186:189], v241 offset:22528
	ds_read_b128 v[204:207], v241 offset:23552
	global_load_lds_dwordx4 v[208:209], off
	s_add_i32 m0, s18, 0x2000
	s_add_u32 s18, s36, 0xb0000
	v_lshl_add_u64 v[210:211], s[36:37], 0, v[196:197]
	s_addc_u32 s19, s37, 0
	s_add_i32 s61, s53, s40
	global_load_lds_dwordx4 v[210:211], off
	v_lshl_add_u64 v[212:213], s[18:19], 0, v[192:193]
	s_mov_b32 m0, s61
	v_lshl_add_u64 v[214:215], s[38:39], 0, v[194:195]
	global_load_lds_dwordx4 v[212:213], off
	v_lshl_add_u64 v[212:213], s[18:19], 0, v[196:197]
	s_add_i32 m0, s61, 0x2000
	s_nop 0
	global_load_lds_dwordx4 v[212:213], off
	v_lshl_add_u64 v[212:213], s[38:39], 0, v[190:191]
	s_mov_b32 m0, s41
	s_nop 0
	global_load_lds_dwordx4 v[212:213], off
	s_mov_b32 m0, s42
	s_nop 0
	global_load_lds_dwordx4 v[214:215], off
	s_waitcnt vmcnt(8)
	s_waitcnt lgkmcnt(0)
	s_barrier
; #define PG8_STAGE(bufoff, gbase, voff) do { _Pragma("unroll") for (int _i = 0; _i < 2; ++_i) \
;         __builtin_amdgcn_global_load_lds((const unsigned*)((const char*)(gbase) + (voff)[_i]), (PG8_LAS unsigned*)(lds + (bufoff) + ldsw + _i * 8192), 16, 0, 0); } while (0)
; #define PG8_LDA(dst, b, h) do { _Pragma("unroll") for (int m = 0; m < 4; ++m) _Pragma("unroll") for (int k = 0; k < 2; ++k) dst[m][k] = *(const PG8_LAS bf16x8*)(lds + PG8_SA(b, h) + aoff + m * 2048 + k * 1024); } while (0)
; #define PG8_LDB(dst, b, h) do { _Pragma("unroll") for (int n = 0; n < 2; ++n) _Pragma("unroll") for (int k = 0; k < 2; ++k) dst[n][k] = *(const PG8_LAS bf16x8*)(lds + PG8_SB(b, h) + boff + n * 2048 + k * 1024); } while (0)
; #define PG8_MMA(ai, bj, At, Bt) do { __builtin_amdgcn_s_setprio(1); _Pragma("unroll") for (int m = 0; m < 4; ++m) _Pragma("unroll") for (int n = 0; n < 2; ++n) _Pragma("unroll") for (int k = 0; k < 2; ++k) \
;         acc[ai][bj][m][n] = __builtin_amdgcn_mfma_f32_16x16x32_bf16(Bt[n][k], At[m][k], acc[ai][bj][m][n], 0, 0, 0); __builtin_amdgcn_s_setprio(0); } while (0)
; #define PG8_WAIT_V(n) asm volatile("s_waitcnt vmcnt(" #n ")" ::: "memory")
; #define PG8_WAIT_L(n) asm volatile("s_waitcnt lgkmcnt(" #n ")" ::: "memory")
; #define PG8_BAR __builtin_amdgcn_s_barrier()
; #define PG8_SCHED __builtin_amdgcn_sched_barrier(0)
; template <class Epi, class Sched, bool ALIGN_EPI = false, bool SP2 = false>
; __device__ __forceinline__ void gemm_phase(PG8_LAS unsigned char* lds, const Gemm g, const Sched& S, const Epi& E) {
;     ...
;             PG8_WAIT_V(8); PG8_WAIT_L(0); PG8_BAR; PG8_MMA(1, 0, At, B0); PG8_MMA(1, 1, At, B1); PG8_BAR; PG8_SCHED;
;             PG8_LDB(B0, 1, 0); PG8_LDB(B1, 1, 1); PG8_SCHED; PG8_LDA(At, 1, 0); PG8_STAGE(PG8_SA(0, 1), a2 + hstep, voffA);
;             PG8_WAIT_V(8); PG8_WAIT_L(0); PG8_BAR; PG8_MMA(0, 0, At, B0); PG8_MMA(0, 1, At, B1); PG8_BAR; PG8_SCHED;
	s_setprio 1
	s_waitcnt lgkmcnt(0)
	v_mfma_f32_16x16x32_bf16 v[62:65], v[98:101], v[162:165], v[62:65]
	v_mfma_f32_16x16x32_bf16 v[58:61], v[122:125], v[162:165], v[58:61]
	v_mfma_f32_16x16x32_bf16 v[46:49], v[98:101], v[170:173], v[46:49]
	v_mfma_f32_16x16x32_bf16 v[42:45], v[122:125], v[170:173], v[42:45]
	v_mfma_f32_16x16x32_bf16 v[30:33], v[98:101], v[178:181], v[30:33]
	v_mfma_f32_16x16x32_bf16 v[26:29], v[122:125], v[178:181], v[26:29]
	v_mfma_f32_16x16x32_bf16 v[14:17], v[98:101], v[186:189], v[14:17]
	v_mfma_f32_16x16x32_bf16 v[10:13], v[122:125], v[186:189], v[10:13]
	v_mfma_f32_16x16x32_bf16 v[62:65], v[110:113], v[166:169], v[62:65]
	v_mfma_f32_16x16x32_bf16 v[58:61], v[134:137], v[166:169], v[58:61]
	v_mfma_f32_16x16x32_bf16 v[46:49], v[110:113], v[174:177], v[46:49]
	v_mfma_f32_16x16x32_bf16 v[42:45], v[134:137], v[174:177], v[42:45]
	v_mfma_f32_16x16x32_bf16 v[30:33], v[110:113], v[182:185], v[30:33]
	v_mfma_f32_16x16x32_bf16 v[26:29], v[134:137], v[182:185], v[26:29]
	v_mfma_f32_16x16x32_bf16 v[14:17], v[110:113], v[204:207], v[14:17]
	v_mfma_f32_16x16x32_bf16 v[10:13], v[134:137], v[204:207], v[10:13]
	s_setprio 0
	s_setprio 1
	v_mfma_f32_16x16x32_bf16 v[54:57], v[138:141], v[162:165], v[54:57]
	v_mfma_f32_16x16x32_bf16 v[50:53], v[146:149], v[162:165], v[50:53]
	v_mfma_f32_16x16x32_bf16 v[38:41], v[138:141], v[170:173], v[38:41]
	v_mfma_f32_16x16x32_bf16 v[34:37], v[146:149], v[170:173], v[34:37]
	v_mfma_f32_16x16x32_bf16 v[22:25], v[138:141], v[178:181], v[22:25]
	v_mfma_f32_16x16x32_bf16 v[18:21], v[146:149], v[178:181], v[18:21]
	v_mfma_f32_16x16x32_bf16 v[6:9], v[138:141], v[186:189], v[6:9]
	v_mfma_f32_16x16x32_bf16 v[2:5], v[146:149], v[186:189], v[2:5]
	v_mfma_f32_16x16x32_bf16 v[54:57], v[142:145], v[166:169], v[54:57]
	v_mfma_f32_16x16x32_bf16 v[50:53], v[150:153], v[166:169], v[50:53]
	v_mfma_f32_16x16x32_bf16 v[38:41], v[142:145], v[174:177], v[38:41]
	v_mfma_f32_16x16x32_bf16 v[34:37], v[150:153], v[174:177], v[34:37]
	v_mfma_f32_16x16x32_bf16 v[22:25], v[142:145], v[182:185], v[22:25]
	v_mfma_f32_16x16x32_bf16 v[18:21], v[150:153], v[182:185], v[18:21]
	v_mfma_f32_16x16x32_bf16 v[6:9], v[142:145], v[204:207], v[6:9]
	v_mfma_f32_16x16x32_bf16 v[2:5], v[150:153], v[204:207], v[2:5]
	s_setprio 0
	s_barrier
	s_add_i32 s61, 0, 0x18000
	s_add_i32 s62, 0, 0x1c000
	v_add_u32_e32 v134, s61, v237
	v_add_u32_e32 v150, s62, v237
	ds_read_b128 v[98:101], v134
	ds_read_b128 v[110:113], v134 offset:1024
	ds_read_b128 v[122:125], v134 offset:2048
	ds_read_b128 v[134:137], v134 offset:3072
	ds_read_b128 v[138:141], v150
	ds_read_b128 v[142:145], v150 offset:1024
	ds_read_b128 v[146:149], v150 offset:2048
	ds_read_b128 v[150:153], v150 offset:3072
	s_add_u32 s18, s38, 0xb0000
	s_addc_u32 s19, s39, 0
	s_mov_b32 m0, s43
	v_lshl_add_u64 v[216:217], s[18:19], 0, v[190:191]
	ds_read_b128 v[162:165], v241 offset:32768
	ds_read_b128 v[166:169], v241 offset:33792
	ds_read_b128 v[170:173], v241 offset:34816
	ds_read_b128 v[174:177], v241 offset:35840
	ds_read_b128 v[178:181], v241 offset:36864
	ds_read_b128 v[182:185], v241 offset:37888
	ds_read_b128 v[186:189], v241 offset:38912
	ds_read_b128 v[204:207], v241 offset:39936
	global_load_lds_dwordx4 v[216:217], off
	v_lshl_add_u64 v[216:217], s[18:19], 0, v[194:195]
	s_mov_b32 m0, s44
	s_nop 0
	global_load_lds_dwordx4 v[216:217], off
	s_waitcnt vmcnt(8)
	s_waitcnt lgkmcnt(0)
	s_barrier
	s_setprio 1
	s_waitcnt lgkmcnt(0)
	v_mfma_f32_16x16x32_bf16 v[158:161], v[98:101], v[162:165], v[158:161]
	v_mfma_f32_16x16x32_bf16 v[154:157], v[122:125], v[162:165], v[154:157]
	v_mfma_f32_16x16x32_bf16 v[118:121], v[98:101], v[170:173], v[118:121]
	v_mfma_f32_16x16x32_bf16 v[114:117], v[122:125], v[170:173], v[114:117]
	v_mfma_f32_16x16x32_bf16 v[94:97], v[98:101], v[178:181], v[94:97]
	v_mfma_f32_16x16x32_bf16 v[90:93], v[122:125], v[178:181], v[90:93]
	v_mfma_f32_16x16x32_bf16 v[78:81], v[98:101], v[186:189], v[78:81]
	v_mfma_f32_16x16x32_bf16 v[74:77], v[122:125], v[186:189], v[74:77]
	v_mfma_f32_16x16x32_bf16 v[158:161], v[110:113], v[166:169], v[158:161]
	v_mfma_f32_16x16x32_bf16 v[154:157], v[134:137], v[166:169], v[154:157]
	v_mfma_f32_16x16x32_bf16 v[118:121], v[110:113], v[174:177], v[118:121]
	v_mfma_f32_16x16x32_bf16 v[114:117], v[134:137], v[174:177], v[114:117]
	v_mfma_f32_16x16x32_bf16 v[94:97], v[110:113], v[182:185], v[94:97]
	v_mfma_f32_16x16x32_bf16 v[90:93], v[134:137], v[182:185], v[90:93]
	v_mfma_f32_16x16x32_bf16 v[78:81], v[110:113], v[204:207], v[78:81]
	v_mfma_f32_16x16x32_bf16 v[74:77], v[134:137], v[204:207], v[74:77]
	s_setprio 0
	s_setprio 1
	v_mfma_f32_16x16x32_bf16 v[130:133], v[138:141], v[162:165], v[130:133]
	v_mfma_f32_16x16x32_bf16 v[126:129], v[146:149], v[162:165], v[126:129]
	v_mfma_f32_16x16x32_bf16 v[106:109], v[138:141], v[170:173], v[106:109]
	v_mfma_f32_16x16x32_bf16 v[102:105], v[146:149], v[170:173], v[102:105]
	v_mfma_f32_16x16x32_bf16 v[86:89], v[138:141], v[178:181], v[86:89]
	v_mfma_f32_16x16x32_bf16 v[82:85], v[146:149], v[178:181], v[82:85]
	v_mfma_f32_16x16x32_bf16 v[70:73], v[138:141], v[186:189], v[70:73]
	v_mfma_f32_16x16x32_bf16 v[66:69], v[146:149], v[186:189], v[66:69]
	v_mfma_f32_16x16x32_bf16 v[130:133], v[142:145], v[166:169], v[130:133]
	v_mfma_f32_16x16x32_bf16 v[126:129], v[150:153], v[166:169], v[126:129]
	v_mfma_f32_16x16x32_bf16 v[106:109], v[142:145], v[174:177], v[106:109]
	v_mfma_f32_16x16x32_bf16 v[102:105], v[150:153], v[174:177], v[102:105]
	v_mfma_f32_16x16x32_bf16 v[86:89], v[142:145], v[182:185], v[86:89]
	v_mfma_f32_16x16x32_bf16 v[82:85], v[150:153], v[182:185], v[82:85]
	v_mfma_f32_16x16x32_bf16 v[70:73], v[142:145], v[204:207], v[70:73]
	v_mfma_f32_16x16x32_bf16 v[66:69], v[150:153], v[204:207], v[66:69]
	s_setprio 0
	s_barrier
; #define PG8_STAGE(bufoff, gbase, voff) do { _Pragma("unroll") for (int _i = 0; _i < 2; ++_i) \
;         __builtin_amdgcn_global_load_lds((const unsigned*)((const char*)(gbase) + (voff)[_i]), (PG8_LAS unsigned*)(lds + (bufoff) + ldsw + _i * 8192), 16, 0, 0); } while (0)
; #define PG8_LDA(dst, b, h) do { _Pragma("unroll") for (int m = 0; m < 4; ++m) _Pragma("unroll") for (int k = 0; k < 2; ++k) dst[m][k] = *(const PG8_LAS bf16x8*)(lds + PG8_SA(b, h) + aoff + m * 2048 + k * 1024); } while (0)
; #define PG8_LDB(dst, b, h) do { _Pragma("unroll") for (int n = 0; n < 2; ++n) _Pragma("unroll") for (int k = 0; k < 2; ++k) dst[n][k] = *(const PG8_LAS bf16x8*)(lds + PG8_SB(b, h) + boff + n * 2048 + k * 1024); } while (0)
; template <class Epi, class Sched, bool ALIGN_EPI = false, bool SP2 = false>
; __device__ __forceinline__ void gemm_phase(PG8_LAS unsigned char* lds, const Gemm g, const Sched& S, const Epi& E) {
;     ...
;         for (int t = 0; t < nt; t += 2) {
;             const bool last = (t == nt - 2);
;             const char* a1 = cA + (size_t)(t + 1) * kstep;
;             const char* a2 = last ? nA : cA + (size_t)(t + 2) * kstep; const char* b2 = last ? nB : cB + (size_t)(t + 2) * kstep;
;             const char* a3 = a2 + kstep; const char* b3 = b2 + kstep;
;             if (last && has_next) S.a_ready(nxt);
;             if constexpr (SP2) {
;             PG8_LDB(B0, 0, 0); PG8_LDB(B1, 0, 1); PG8_SCHED; PG8_LDA(At, 0, 0); PG8_STAGE(PG8_SA(1, 1), a1 + hstep, voffA);
;             PG8_WAIT_V(8); PG8_WAIT_L(0); PG8_BAR; PG8_MMA(0, 0, At, B0); PG8_MMA(0, 1, At, B1); PG8_BAR; PG8_SCHED;
;             PG8_LDA(At, 0, 1); PG8_STAGE(PG8_SB(0, 0), b2, voffB); PG8_STAGE(PG8_SB(0, 1), b2 + hstep, voffB); PG8_STAGE(PG8_SA(0, 0), a2, voffA);
;             PG8_WAIT_V(8); PG8_WAIT_L(0); PG8_BAR; PG8_MMA(1, 0, At, B0); PG8_MMA(1, 1, At, B1); PG8_BAR; PG8_SCHED;
;             PG8_LDB(B0, 1, 0); PG8_LDB(B1, 1, 1); PG8_SCHED; PG8_LDA(At, 1, 0); PG8_STAGE(PG8_SA(0, 1), a2 + hstep, voffA);
;             PG8_WAIT_V(8); PG8_WAIT_L(0); PG8_BAR; PG8_MMA(0, 0, At, B0); PG8_MMA(0, 1, At, B1); PG8_BAR; PG8_SCHED;
;             PG8_LDA(At, 1, 1); PG8_STAGE(PG8_SB(1, 0), b3, voffB); PG8_STAGE(PG8_SB(1, 1), b3 + hstep, voffB); PG8_STAGE(PG8_SA(1, 0), a3, voffA);
;             PG8_WAIT_V(8); PG8_WAIT_L(0); PG8_BAR; PG8_MMA(1, 0, At, B0); PG8_MMA(1, 1, At, B1); PG8_BAR; PG8_SCHED;
	s_add_i32 s18, s61, s40
	v_lshl_add_u64 v[208:209], v[208:209], 0, s[16:17]
	s_mov_b32 m0, s18
	ds_read_b128 v[162:165], v241 offset:49152
	ds_read_b128 v[166:169], v241 offset:50176
	ds_read_b128 v[170:173], v241 offset:51200
	ds_read_b128 v[174:177], v241 offset:52224
	ds_read_b128 v[178:181], v241 offset:53248
	ds_read_b128 v[182:185], v241 offset:54272
	ds_read_b128 v[186:189], v241 offset:55296
	ds_read_b128 v[204:207], v241 offset:56320
	global_load_lds_dwordx4 v[208:209], off
	s_add_i32 m0, s18, 0x2000
	s_add_u32 s18, s36, 0xb0080
	v_lshl_add_u64 v[208:209], v[210:211], 0, s[16:17]
	s_addc_u32 s19, s37, 0
	s_add_i32 s36, s62, s40
	global_load_lds_dwordx4 v[208:209], off
	v_lshl_add_u64 v[208:209], s[18:19], 0, v[192:193]
	s_mov_b32 m0, s36
	s_nop 0
	global_load_lds_dwordx4 v[208:209], off
	v_lshl_add_u64 v[208:209], s[18:19], 0, v[196:197]
	s_add_i32 m0, s36, 0x2000
	s_nop 0
	global_load_lds_dwordx4 v[208:209], off
	v_lshl_add_u64 v[208:209], v[212:213], 0, s[16:17]
	s_mov_b32 m0, s46
	s_nop 0
	global_load_lds_dwordx4 v[208:209], off
	v_lshl_add_u64 v[208:209], v[214:215], 0, s[16:17]
	s_mov_b32 m0, s47
	s_nop 0
	global_load_lds_dwordx4 v[208:209], off
	s_waitcnt vmcnt(8)
	s_waitcnt lgkmcnt(0)
	s_barrier
	s_setprio 1
	s_waitcnt lgkmcnt(0)
	v_mfma_f32_16x16x32_bf16 v[62:65], v[98:101], v[162:165], v[62:65]
	v_mfma_f32_16x16x32_bf16 v[58:61], v[122:125], v[162:165], v[58:61]
	v_mfma_f32_16x16x32_bf16 v[46:49], v[98:101], v[170:173], v[46:49]
	v_mfma_f32_16x16x32_bf16 v[42:45], v[122:125], v[170:173], v[42:45]
	v_mfma_f32_16x16x32_bf16 v[30:33], v[98:101], v[178:181], v[30:33]
	v_mfma_f32_16x16x32_bf16 v[26:29], v[122:125], v[178:181], v[26:29]
	v_mfma_f32_16x16x32_bf16 v[14:17], v[98:101], v[186:189], v[14:17]
	v_mfma_f32_16x16x32_bf16 v[10:13], v[122:125], v[186:189], v[10:13]
	v_mfma_f32_16x16x32_bf16 v[62:65], v[110:113], v[166:169], v[62:65]
	v_mfma_f32_16x16x32_bf16 v[58:61], v[134:137], v[166:169], v[58:61]
	v_mfma_f32_16x16x32_bf16 v[46:49], v[110:113], v[174:177], v[46:49]
	v_mfma_f32_16x16x32_bf16 v[42:45], v[134:137], v[174:177], v[42:45]
	v_mfma_f32_16x16x32_bf16 v[30:33], v[110:113], v[182:185], v[30:33]
	v_mfma_f32_16x16x32_bf16 v[26:29], v[134:137], v[182:185], v[26:29]
	v_mfma_f32_16x16x32_bf16 v[14:17], v[110:113], v[204:207], v[14:17]
	v_mfma_f32_16x16x32_bf16 v[10:13], v[134:137], v[204:207], v[10:13]
	s_setprio 0
	s_setprio 1
	v_mfma_f32_16x16x32_bf16 v[54:57], v[138:141], v[162:165], v[54:57]
	v_mfma_f32_16x16x32_bf16 v[50:53], v[146:149], v[162:165], v[50:53]
	v_mfma_f32_16x16x32_bf16 v[38:41], v[138:141], v[170:173], v[38:41]
	v_mfma_f32_16x16x32_bf16 v[34:37], v[146:149], v[170:173], v[34:37]
	v_mfma_f32_16x16x32_bf16 v[22:25], v[138:141], v[178:181], v[22:25]
	v_mfma_f32_16x16x32_bf16 v[18:21], v[146:149], v[178:181], v[18:21]
	v_mfma_f32_16x16x32_bf16 v[6:9], v[138:141], v[186:189], v[6:9]
	v_mfma_f32_16x16x32_bf16 v[2:5], v[146:149], v[186:189], v[2:5]
	v_mfma_f32_16x16x32_bf16 v[54:57], v[142:145], v[166:169], v[54:57]
	v_mfma_f32_16x16x32_bf16 v[50:53], v[150:153], v[166:169], v[50:53]
	v_mfma_f32_16x16x32_bf16 v[38:41], v[142:145], v[174:177], v[38:41]
	v_mfma_f32_16x16x32_bf16 v[34:37], v[150:153], v[174:177], v[34:37]
	v_mfma_f32_16x16x32_bf16 v[22:25], v[142:145], v[182:185], v[22:25]
	v_mfma_f32_16x16x32_bf16 v[18:21], v[150:153], v[182:185], v[18:21]
	v_mfma_f32_16x16x32_bf16 v[6:9], v[142:145], v[204:207], v[6:9]
	v_mfma_f32_16x16x32_bf16 v[2:5], v[150:153], v[204:207], v[2:5]
	s_setprio 0
	s_barrier
	s_add_i32 s60, s60, 2
	s_add_u32 s34, s34, 0x100
	s_addc_u32 s35, s35, 0
	s_add_u32 s58, s58, 0x100
	s_addc_u32 s59, s59, 0
	s_cmp_gt_u32 s60, 41
	s_cbranch_scc1 .Lrp_gen_p5
	s_cmp_lg_u32 s60, 40
	s_cbranch_scc1 .LBB0_892
	s_cmpk_lg_i32 s33, 0x100
	s_cbranch_scc1 .LBB0_892
	ds_read_b128 v[98:101], v239
	ds_read_b128 v[110:113], v239 offset:1024
	ds_read_b128 v[122:125], v239 offset:2048
	ds_read_b128 v[134:137], v239 offset:3072
	ds_read_b128 v[138:141], v240
	ds_read_b128 v[142:145], v240 offset:1024
	ds_read_b128 v[146:149], v240 offset:2048
	ds_read_b128 v[150:153], v240 offset:3072
	s_add_u32 s18, s34, 0xfff50080
	s_addc_u32 s19, s35, -1
	s_cmp_eq_u32 s60, 40
	s_cselect_b32 s39, s1, s19
	s_cselect_b32 s38, s0, s18
	s_cselect_b32 s37, s31, s59
	s_cselect_b32 s36, s30, s58
	v_lshl_add_u64 v[208:209], s[34:35], 0, v[198:199]
	s_add_i32 m0, s41, 0xc000
	ds_read_b128 v[162:165], v241
	ds_read_b128 v[166:169], v241 offset:1024
	ds_read_b128 v[170:173], v241 offset:2048
	ds_read_b128 v[174:177], v241 offset:3072
	ds_read_b128 v[178:181], v241 offset:4096
	ds_read_b128 v[182:185], v241 offset:5120
	ds_read_b128 v[186:189], v241 offset:6144
	ds_read_b128 v[204:207], v241 offset:7168
	global_load_lds_dwordx4 v[208:209], off
	v_lshl_add_u64 v[208:209], s[34:35], 0, v[200:201]
	s_add_i32 m0, s41, 0xe000
	s_nop 0
	global_load_lds_dwordx4 v[208:209], off
	v_lshl_or_b32 v255, s12, 8, v238
	v_lshl_add_u32 v235, s57, 8, v1
	v_lshlrev_b32_e32 v255, 1, v255
	v_lshl_add_u32 v255, v235, 11, v255
	s_mov_b64 s[84:85], s[20:21]
	global_load_dwordx4 v[242:245], v255, s[84:85]
	global_load_dwordx4 v[208:211], v255, s[84:85] offset:256
	s_add_u32 s84, s20, 0x8000
	s_addc_u32 s85, s21, 0
	global_load_dwordx4 v[212:215], v255, s[84:85]
	global_load_dwordx4 v[216:219], v255, s[84:85] offset:256
	s_add_u32 s84, s20, 0x10000
	s_addc_u32 s85, s21, 0
	global_load_dwordx4 v[220:223], v255, s[84:85]
	global_load_dwordx4 v[224:227], v255, s[84:85] offset:256
	s_add_u32 s84, s20, 0x18000
	s_addc_u32 s85, s21, 0
	global_load_dwordx4 v[228:231], v255, s[84:85]
	global_load_dwordx4 v[232:235], v255, s[84:85] offset:256
	s_add_u32 s84, s20, 0x40000
	s_addc_u32 s85, s21, 0
	global_load_dwordx4 v[246:249], v255, s[84:85]
	global_load_dwordx4 v[250:253], v255, s[84:85] offset:256
	s_waitcnt vmcnt(18)
	s_waitcnt lgkmcnt(0)
	s_barrier
; #define PG8_STAGE(bufoff, gbase, voff) do { _Pragma("unroll") for (int _i = 0; _i < 2; ++_i) \
;         __builtin_amdgcn_global_load_lds((const unsigned*)((const char*)(gbase) + (voff)[_i]), (PG8_LAS unsigned*)(lds + (bufoff) + ldsw + _i * 8192), 16, 0, 0); } while (0)
; #define PG8_LDA(dst, b, h) do { _Pragma("unroll") for (int m = 0; m < 4; ++m) _Pragma("unroll") for (int k = 0; k < 2; ++k) dst[m][k] = *(const PG8_LAS bf16x8*)(lds + PG8_SA(b, h) + aoff + m * 2048 + k * 1024); } while (0)
; #define PG8_LDB(dst, b, h) do { _Pragma("unroll") for (int n = 0; n < 2; ++n) _Pragma("unroll") for (int k = 0; k < 2; ++k) dst[n][k] = *(const PG8_LAS bf16x8*)(lds + PG8_SB(b, h) + boff + n * 2048 + k * 1024); } while (0)
; #define PG8_MMA(ai, bj, At, Bt) do { __builtin_amdgcn_s_setprio(1); _Pragma("unroll") for (int m = 0; m < 4; ++m) _Pragma("unroll") for (int n = 0; n < 2; ++n) _Pragma("unroll") for (int k = 0; k < 2; ++k) \
;         acc[ai][bj][m][n] = __builtin_amdgcn_mfma_f32_16x16x32_bf16(Bt[n][k], At[m][k], acc[ai][bj][m][n], 0, 0, 0); __builtin_amdgcn_s_setprio(0); } while (0)
; #define PG8_WAIT_V(n) asm volatile("s_waitcnt vmcnt(" #n ")" ::: "memory")
; template <class Epi, class Sched, bool ALIGN_EPI = false, bool SP2 = false>
; __device__ __forceinline__ void gemm_phase(PG8_LAS unsigned char* lds, const Gemm g, const Sched& S, const Epi& E) {
;     ...
;             PG8_LDB(B0, 0, 0); PG8_LDB(B1, 0, 1); PG8_SCHED; PG8_LDA(At, 0, 0); PG8_STAGE(PG8_SA(1, 1), a1 + hstep, voffA);
;             PG8_WAIT_V(8); PG8_WAIT_L(0); PG8_BAR; PG8_MMA(0, 0, At, B0); PG8_MMA(0, 1, At, B1); PG8_BAR; PG8_SCHED;
;             PG8_LDA(At, 0, 1); PG8_STAGE(PG8_SB(0, 0), b2, voffB); PG8_STAGE(PG8_SB(0, 1), b2 + hstep, voffB); PG8_STAGE(PG8_SA(0, 0), a2, voffA);
;             PG8_WAIT_V(8); PG8_WAIT_L(0); PG8_BAR; PG8_MMA(1, 0, At, B0); PG8_MMA(1, 1, At, B1); PG8_BAR; PG8_SCHED;
;             PG8_LDB(B0, 1, 0); PG8_LDB(B1, 1, 1); PG8_SCHED; PG8_LDA(At, 1, 0); PG8_STAGE(PG8_SA(0, 1), a2 + hstep, voffA);
;             PG8_WAIT_V(8); PG8_WAIT_L(0); PG8_BAR; PG8_MMA(0, 0, At, B0); PG8_MMA(0, 1, At, B1); PG8_BAR; PG8_SCHED;
;             PG8_LDA(At, 1, 1); PG8_STAGE(PG8_SB(1, 0), b3, voffB); PG8_STAGE(PG8_SB(1, 1), b3 + hstep, voffB); PG8_STAGE(PG8_SA(1, 0), a3, voffA);
;             PG8_WAIT_V(8); PG8_WAIT_L(0); PG8_BAR; PG8_MMA(1, 0, At, B0); PG8_MMA(1, 1, At, B1); PG8_BAR; PG8_SCHED;
	s_setprio 1
	s_waitcnt lgkmcnt(0)
	v_mfma_f32_16x16x32_bf16 v[158:161], v[98:101], v[162:165], v[158:161]
	v_mfma_f32_16x16x32_bf16 v[154:157], v[122:125], v[162:165], v[154:157]
	v_mfma_f32_16x16x32_bf16 v[118:121], v[98:101], v[170:173], v[118:121]
	v_mfma_f32_16x16x32_bf16 v[114:117], v[122:125], v[170:173], v[114:117]
	v_mfma_f32_16x16x32_bf16 v[94:97], v[98:101], v[178:181], v[94:97]
	v_mfma_f32_16x16x32_bf16 v[90:93], v[122:125], v[178:181], v[90:93]
	v_mfma_f32_16x16x32_bf16 v[78:81], v[98:101], v[186:189], v[78:81]
	v_mfma_f32_16x16x32_bf16 v[74:77], v[122:125], v[186:189], v[74:77]
	v_mfma_f32_16x16x32_bf16 v[158:161], v[110:113], v[166:169], v[158:161]
	v_mfma_f32_16x16x32_bf16 v[154:157], v[134:137], v[166:169], v[154:157]
	v_mfma_f32_16x16x32_bf16 v[118:121], v[110:113], v[174:177], v[118:121]
	v_mfma_f32_16x16x32_bf16 v[114:117], v[134:137], v[174:177], v[114:117]
	v_mfma_f32_16x16x32_bf16 v[94:97], v[110:113], v[182:185], v[94:97]
	v_mfma_f32_16x16x32_bf16 v[90:93], v[134:137], v[182:185], v[90:93]
	v_mfma_f32_16x16x32_bf16 v[78:81], v[110:113], v[204:207], v[78:81]
	v_mfma_f32_16x16x32_bf16 v[74:77], v[134:137], v[204:207], v[74:77]
	s_setprio 0
	s_setprio 1
	v_mfma_f32_16x16x32_bf16 v[130:133], v[138:141], v[162:165], v[130:133]
	v_mfma_f32_16x16x32_bf16 v[126:129], v[146:149], v[162:165], v[126:129]
	v_mfma_f32_16x16x32_bf16 v[106:109], v[138:141], v[170:173], v[106:109]
	v_mfma_f32_16x16x32_bf16 v[102:105], v[146:149], v[170:173], v[102:105]
	v_mfma_f32_16x16x32_bf16 v[86:89], v[138:141], v[178:181], v[86:89]
	v_mfma_f32_16x16x32_bf16 v[82:85], v[146:149], v[178:181], v[82:85]
	v_mfma_f32_16x16x32_bf16 v[70:73], v[138:141], v[186:189], v[70:73]
	v_mfma_f32_16x16x32_bf16 v[66:69], v[146:149], v[186:189], v[66:69]
	v_mfma_f32_16x16x32_bf16 v[130:133], v[142:145], v[166:169], v[130:133]
	v_mfma_f32_16x16x32_bf16 v[126:129], v[150:153], v[166:169], v[126:129]
	v_mfma_f32_16x16x32_bf16 v[106:109], v[142:145], v[174:177], v[106:109]
	v_mfma_f32_16x16x32_bf16 v[102:105], v[150:153], v[174:177], v[102:105]
	v_mfma_f32_16x16x32_bf16 v[86:89], v[142:145], v[182:185], v[86:89]
	v_mfma_f32_16x16x32_bf16 v[82:85], v[150:153], v[182:185], v[82:85]
	v_mfma_f32_16x16x32_bf16 v[70:73], v[142:145], v[204:207], v[70:73]
	v_mfma_f32_16x16x32_bf16 v[66:69], v[150:153], v[204:207], v[66:69]
	s_setprio 0
	s_barrier
	s_add_i32 s18, s52, s40
	s_mov_b32 m0, s18
	ds_read_b128 v[162:165], v241 offset:16384
	ds_read_b128 v[166:169], v241 offset:17408
	ds_read_b128 v[170:173], v241 offset:18432
	ds_read_b128 v[174:177], v241 offset:19456
	ds_read_b128 v[178:181], v241 offset:20480
	ds_read_b128 v[182:185], v241 offset:21504
	ds_read_b128 v[186:189], v241 offset:22528
	ds_read_b128 v[204:207], v241 offset:23552
	s_add_i32 m0, s18, 0x2000
	s_add_u32 s18, s36, 0xb0000
	s_addc_u32 s19, s37, 0
	s_add_i32 s61, s53, s40
	s_mov_b32 m0, s61
	s_add_i32 m0, s61, 0x2000
	s_nop 0
	s_mov_b32 m0, s41
	s_nop 0
	s_mov_b32 m0, s42
	s_nop 0
	s_waitcnt vmcnt(12)
	s_waitcnt lgkmcnt(0)
	s_barrier
	s_setprio 1
	s_waitcnt lgkmcnt(0)
	v_mfma_f32_16x16x32_bf16 v[62:65], v[98:101], v[162:165], v[62:65]
	v_mfma_f32_16x16x32_bf16 v[58:61], v[122:125], v[162:165], v[58:61]
	v_mfma_f32_16x16x32_bf16 v[46:49], v[98:101], v[170:173], v[46:49]
	v_mfma_f32_16x16x32_bf16 v[42:45], v[122:125], v[170:173], v[42:45]
	v_mfma_f32_16x16x32_bf16 v[30:33], v[98:101], v[178:181], v[30:33]
	v_mfma_f32_16x16x32_bf16 v[26:29], v[122:125], v[178:181], v[26:29]
	v_mfma_f32_16x16x32_bf16 v[14:17], v[98:101], v[186:189], v[14:17]
	v_mfma_f32_16x16x32_bf16 v[10:13], v[122:125], v[186:189], v[10:13]
	v_mfma_f32_16x16x32_bf16 v[62:65], v[110:113], v[166:169], v[62:65]
	v_mfma_f32_16x16x32_bf16 v[58:61], v[134:137], v[166:169], v[58:61]
	v_mfma_f32_16x16x32_bf16 v[46:49], v[110:113], v[174:177], v[46:49]
	v_mfma_f32_16x16x32_bf16 v[42:45], v[134:137], v[174:177], v[42:45]
	v_mfma_f32_16x16x32_bf16 v[30:33], v[110:113], v[182:185], v[30:33]
	v_mfma_f32_16x16x32_bf16 v[26:29], v[134:137], v[182:185], v[26:29]
	v_mfma_f32_16x16x32_bf16 v[14:17], v[110:113], v[204:207], v[14:17]
	v_mfma_f32_16x16x32_bf16 v[10:13], v[134:137], v[204:207], v[10:13]
	s_setprio 0
	s_setprio 1
	v_mfma_f32_16x16x32_bf16 v[54:57], v[138:141], v[162:165], v[54:57]
	v_mfma_f32_16x16x32_bf16 v[50:53], v[146:149], v[162:165], v[50:53]
	v_mfma_f32_16x16x32_bf16 v[38:41], v[138:141], v[170:173], v[38:41]
	v_mfma_f32_16x16x32_bf16 v[34:37], v[146:149], v[170:173], v[34:37]
	v_mfma_f32_16x16x32_bf16 v[22:25], v[138:141], v[178:181], v[22:25]
	v_mfma_f32_16x16x32_bf16 v[18:21], v[146:149], v[178:181], v[18:21]
	v_mfma_f32_16x16x32_bf16 v[6:9], v[138:141], v[186:189], v[6:9]
	v_mfma_f32_16x16x32_bf16 v[2:5], v[146:149], v[186:189], v[2:5]
	v_mfma_f32_16x16x32_bf16 v[54:57], v[142:145], v[166:169], v[54:57]
	v_mfma_f32_16x16x32_bf16 v[50:53], v[150:153], v[166:169], v[50:53]
	v_mfma_f32_16x16x32_bf16 v[38:41], v[142:145], v[174:177], v[38:41]
	v_mfma_f32_16x16x32_bf16 v[34:37], v[150:153], v[174:177], v[34:37]
	v_mfma_f32_16x16x32_bf16 v[22:25], v[142:145], v[182:185], v[22:25]
	v_mfma_f32_16x16x32_bf16 v[18:21], v[150:153], v[182:185], v[18:21]
	v_mfma_f32_16x16x32_bf16 v[6:9], v[142:145], v[204:207], v[6:9]
	v_mfma_f32_16x16x32_bf16 v[2:5], v[150:153], v[204:207], v[2:5]
	s_setprio 0
	s_barrier
; #define PG8_STAGE(bufoff, gbase, voff) do { _Pragma("unroll") for (int _i = 0; _i < 2; ++_i) \
;         __builtin_amdgcn_global_load_lds((const unsigned*)((const char*)(gbase) + (voff)[_i]), (PG8_LAS unsigned*)(lds + (bufoff) + ldsw + _i * 8192), 16, 0, 0); } while (0)
; #define PG8_LDA(dst, b, h) do { _Pragma("unroll") for (int m = 0; m < 4; ++m) _Pragma("unroll") for (int k = 0; k < 2; ++k) dst[m][k] = *(const PG8_LAS bf16x8*)(lds + PG8_SA(b, h) + aoff + m * 2048 + k * 1024); } while (0)
; #define PG8_LDB(dst, b, h) do { _Pragma("unroll") for (int n = 0; n < 2; ++n) _Pragma("unroll") for (int k = 0; k < 2; ++k) dst[n][k] = *(const PG8_LAS bf16x8*)(lds + PG8_SB(b, h) + boff + n * 2048 + k * 1024); } while (0)
; #define PG8_MMA(ai, bj, At, Bt) do { __builtin_amdgcn_s_setprio(1); _Pragma("unroll") for (int m = 0; m < 4; ++m) _Pragma("unroll") for (int n = 0; n < 2; ++n) _Pragma("unroll") for (int k = 0; k < 2; ++k) \
;         acc[ai][bj][m][n] = __builtin_amdgcn_mfma_f32_16x16x32_bf16(Bt[n][k], At[m][k], acc[ai][bj][m][n], 0, 0, 0); __builtin_amdgcn_s_setprio(0); } while (0)
; #define PG8_WAIT_V(n) asm volatile("s_waitcnt vmcnt(" #n ")" ::: "memory")
; #define PG8_WAIT_L(n) asm volatile("s_waitcnt lgkmcnt(" #n ")" ::: "memory")
; #define PG8_BAR __builtin_amdgcn_s_barrier()
; #define PG8_SCHED __builtin_amdgcn_sched_barrier(0)
; template <class Epi, class Sched, bool ALIGN_EPI = false, bool SP2 = false>
; __device__ __forceinline__ void gemm_phase(PG8_LAS unsigned char* lds, const Gemm g, const Sched& S, const Epi& E) {
;     ...
;             PG8_LDB(B0, 1, 0); PG8_LDB(B1, 1, 1); PG8_SCHED; PG8_LDA(At, 1, 0); PG8_STAGE(PG8_SA(0, 1), a2 + hstep, voffA);
;             PG8_WAIT_V(8); PG8_WAIT_L(0); PG8_BAR; PG8_MMA(0, 0, At, B0); PG8_MMA(0, 1, At, B1); PG8_BAR; PG8_SCHED;
;             PG8_LDA(At, 1, 1); PG8_STAGE(PG8_SB(1, 0), b3, voffB); PG8_STAGE(PG8_SB(1, 1), b3 + hstep, voffB); PG8_STAGE(PG8_SA(1, 0), a3, voffA);
;             PG8_WAIT_V(8); PG8_WAIT_L(0); PG8_BAR; PG8_MMA(1, 0, At, B0); PG8_MMA(1, 1, At, B1); PG8_BAR; PG8_SCHED;
	s_add_i32 s61, 0, 0x18000
	s_add_i32 s62, 0, 0x1c000
	v_add_u32_e32 v134, s61, v237
	v_add_u32_e32 v150, s62, v237
	ds_read_b128 v[98:101], v134
	ds_read_b128 v[110:113], v134 offset:1024
	ds_read_b128 v[122:125], v134 offset:2048
	ds_read_b128 v[134:137], v134 offset:3072
	ds_read_b128 v[138:141], v150
	ds_read_b128 v[142:145], v150 offset:1024
	ds_read_b128 v[146:149], v150 offset:2048
	ds_read_b128 v[150:153], v150 offset:3072
	s_add_u32 s18, s38, 0xb0000
	s_addc_u32 s19, s39, 0
	s_mov_b32 m0, s43
	ds_read_b128 v[162:165], v241 offset:32768
	ds_read_b128 v[166:169], v241 offset:33792
	ds_read_b128 v[170:173], v241 offset:34816
	ds_read_b128 v[174:177], v241 offset:35840
	ds_read_b128 v[178:181], v241 offset:36864
	ds_read_b128 v[182:185], v241 offset:37888
	ds_read_b128 v[186:189], v241 offset:38912
	ds_read_b128 v[204:207], v241 offset:39936
	s_mov_b32 m0, s44
	s_nop 0
	s_waitcnt vmcnt(10)
	s_waitcnt lgkmcnt(0)
	s_barrier
	s_setprio 1
	s_waitcnt lgkmcnt(0)
	v_mfma_f32_16x16x32_bf16 v[158:161], v[98:101], v[162:165], v[158:161]
	v_mfma_f32_16x16x32_bf16 v[154:157], v[122:125], v[162:165], v[154:157]
	v_mfma_f32_16x16x32_bf16 v[118:121], v[98:101], v[170:173], v[118:121]
	v_mfma_f32_16x16x32_bf16 v[114:117], v[122:125], v[170:173], v[114:117]
	v_mfma_f32_16x16x32_bf16 v[94:97], v[98:101], v[178:181], v[94:97]
	v_mfma_f32_16x16x32_bf16 v[90:93], v[122:125], v[178:181], v[90:93]
	v_mfma_f32_16x16x32_bf16 v[78:81], v[98:101], v[186:189], v[78:81]
	v_mfma_f32_16x16x32_bf16 v[74:77], v[122:125], v[186:189], v[74:77]
	v_mfma_f32_16x16x32_bf16 v[158:161], v[110:113], v[166:169], v[158:161]
	v_mfma_f32_16x16x32_bf16 v[154:157], v[134:137], v[166:169], v[154:157]
	v_mfma_f32_16x16x32_bf16 v[118:121], v[110:113], v[174:177], v[118:121]
	v_mfma_f32_16x16x32_bf16 v[114:117], v[134:137], v[174:177], v[114:117]
	v_mfma_f32_16x16x32_bf16 v[94:97], v[110:113], v[182:185], v[94:97]
	v_mfma_f32_16x16x32_bf16 v[90:93], v[134:137], v[182:185], v[90:93]
	v_mfma_f32_16x16x32_bf16 v[78:81], v[110:113], v[204:207], v[78:81]
	v_mfma_f32_16x16x32_bf16 v[74:77], v[134:137], v[204:207], v[74:77]
	s_setprio 0
	s_setprio 1
	v_mfma_f32_16x16x32_bf16 v[130:133], v[138:141], v[162:165], v[130:133]
	v_mfma_f32_16x16x32_bf16 v[126:129], v[146:149], v[162:165], v[126:129]
	v_mfma_f32_16x16x32_bf16 v[106:109], v[138:141], v[170:173], v[106:109]
	v_mfma_f32_16x16x32_bf16 v[102:105], v[146:149], v[170:173], v[102:105]
	v_mfma_f32_16x16x32_bf16 v[86:89], v[138:141], v[178:181], v[86:89]
	v_mfma_f32_16x16x32_bf16 v[82:85], v[146:149], v[178:181], v[82:85]
	v_mfma_f32_16x16x32_bf16 v[70:73], v[138:141], v[186:189], v[70:73]
	v_mfma_f32_16x16x32_bf16 v[66:69], v[146:149], v[186:189], v[66:69]
	v_mfma_f32_16x16x32_bf16 v[130:133], v[142:145], v[166:169], v[130:133]
	v_mfma_f32_16x16x32_bf16 v[126:129], v[150:153], v[166:169], v[126:129]
	v_mfma_f32_16x16x32_bf16 v[106:109], v[142:145], v[174:177], v[106:109]
	v_mfma_f32_16x16x32_bf16 v[102:105], v[150:153], v[174:177], v[102:105]
	v_mfma_f32_16x16x32_bf16 v[86:89], v[142:145], v[182:185], v[86:89]
	v_mfma_f32_16x16x32_bf16 v[82:85], v[150:153], v[182:185], v[82:85]
	v_mfma_f32_16x16x32_bf16 v[70:73], v[142:145], v[204:207], v[70:73]
	v_mfma_f32_16x16x32_bf16 v[66:69], v[150:153], v[204:207], v[66:69]
	s_setprio 0
	s_barrier
	s_add_i32 s18, s61, s40
	s_mov_b32 m0, s18
	ds_read_b128 v[162:165], v241 offset:49152
	ds_read_b128 v[166:169], v241 offset:50176
	ds_read_b128 v[170:173], v241 offset:51200
	ds_read_b128 v[174:177], v241 offset:52224
	ds_read_b128 v[178:181], v241 offset:53248
	ds_read_b128 v[182:185], v241 offset:54272
	ds_read_b128 v[186:189], v241 offset:55296
	ds_read_b128 v[204:207], v241 offset:56320
	s_add_i32 m0, s18, 0x2000
	s_add_u32 s18, s36, 0xb0080
	s_addc_u32 s19, s37, 0
	s_add_i32 s36, s62, s40
	s_mov_b32 m0, s36
	s_nop 0
	s_add_i32 m0, s36, 0x2000
	s_nop 0
	s_mov_b32 m0, s46
	s_nop 0
	s_mov_b32 m0, s47
	s_nop 0
	s_waitcnt vmcnt(10)
	s_waitcnt lgkmcnt(0)
	s_barrier
	s_setprio 1
	s_waitcnt lgkmcnt(0)
	v_mfma_f32_16x16x32_bf16 v[62:65], v[98:101], v[162:165], v[62:65]
	v_mfma_f32_16x16x32_bf16 v[58:61], v[122:125], v[162:165], v[58:61]
	v_mfma_f32_16x16x32_bf16 v[46:49], v[98:101], v[170:173], v[46:49]
	v_mfma_f32_16x16x32_bf16 v[42:45], v[122:125], v[170:173], v[42:45]
	v_mfma_f32_16x16x32_bf16 v[30:33], v[98:101], v[178:181], v[30:33]
	v_mfma_f32_16x16x32_bf16 v[26:29], v[122:125], v[178:181], v[26:29]
	v_mfma_f32_16x16x32_bf16 v[14:17], v[98:101], v[186:189], v[14:17]
	v_mfma_f32_16x16x32_bf16 v[10:13], v[122:125], v[186:189], v[10:13]
	v_mfma_f32_16x16x32_bf16 v[62:65], v[110:113], v[166:169], v[62:65]
	v_mfma_f32_16x16x32_bf16 v[58:61], v[134:137], v[166:169], v[58:61]
	v_mfma_f32_16x16x32_bf16 v[46:49], v[110:113], v[174:177], v[46:49]
	v_mfma_f32_16x16x32_bf16 v[42:45], v[134:137], v[174:177], v[42:45]
	v_mfma_f32_16x16x32_bf16 v[30:33], v[110:113], v[182:185], v[30:33]
	v_mfma_f32_16x16x32_bf16 v[26:29], v[134:137], v[182:185], v[26:29]
	v_mfma_f32_16x16x32_bf16 v[14:17], v[110:113], v[204:207], v[14:17]
	v_mfma_f32_16x16x32_bf16 v[10:13], v[134:137], v[204:207], v[10:13]
	s_setprio 0
	s_setprio 1
	v_mfma_f32_16x16x32_bf16 v[54:57], v[138:141], v[162:165], v[54:57]
	v_mfma_f32_16x16x32_bf16 v[50:53], v[146:149], v[162:165], v[50:53]
	v_mfma_f32_16x16x32_bf16 v[38:41], v[138:141], v[170:173], v[38:41]
	v_mfma_f32_16x16x32_bf16 v[34:37], v[146:149], v[170:173], v[34:37]
	v_mfma_f32_16x16x32_bf16 v[22:25], v[138:141], v[178:181], v[22:25]
	v_mfma_f32_16x16x32_bf16 v[18:21], v[146:149], v[178:181], v[18:21]
	v_mfma_f32_16x16x32_bf16 v[6:9], v[138:141], v[186:189], v[6:9]
	v_mfma_f32_16x16x32_bf16 v[2:5], v[146:149], v[186:189], v[2:5]
	v_mfma_f32_16x16x32_bf16 v[54:57], v[142:145], v[166:169], v[54:57]
	v_mfma_f32_16x16x32_bf16 v[50:53], v[150:153], v[166:169], v[50:53]
	v_mfma_f32_16x16x32_bf16 v[38:41], v[142:145], v[174:177], v[38:41]
	v_mfma_f32_16x16x32_bf16 v[34:37], v[150:153], v[174:177], v[34:37]
	v_mfma_f32_16x16x32_bf16 v[22:25], v[142:145], v[182:185], v[22:25]
	v_mfma_f32_16x16x32_bf16 v[18:21], v[150:153], v[182:185], v[18:21]
	v_mfma_f32_16x16x32_bf16 v[6:9], v[142:145], v[204:207], v[6:9]
	v_mfma_f32_16x16x32_bf16 v[2:5], v[150:153], v[204:207], v[2:5]
	s_setprio 0
	s_barrier
	s_add_i32 s60, s60, 2
	s_add_u32 s34, s34, 0x100
	s_addc_u32 s35, s35, 0
	s_add_u32 s58, s58, 0x100
	s_addc_u32 s59, s59, 0
	s_branch .Lrp_done_p5
;     __device__ __forceinline__ void operator()(const f32x4 (&acc)[2][2][4][2], const Unit& u, int wr, int wc, int fr, int fq) const {
;     ...
;         const int row0 = u.pm * BM + wr * 64 + fr, col0 = u.pn * BM + wc * 32 + 8 * fq;
;         u32x4 bva[2][4][2];
; #pragma unroll
;         for (int ai = 0; ai < 2; ++ai)
; #pragma unroll
;             for (int m = 0; m < 4; ++m)
; #pragma unroll
;                 for (int bj = 0; bj < 2; ++bj) bva[ai][m][bj] = *(const u32x4*)(Xb + (size_t)(row0 + ai * HALF + m * 16) * DM + col0 + bj * HALF);
;         asm volatile("" :: "v"(bva[0][0][0]), "v"(bva[0][1][0]), "v"(bva[0][2][0]), "v"(bva[0][3][0]), "v"(bva[1][0][0]), "v"(bva[1][1][0]), "v"(bva[1][2][0]), "v"(bva[1][3][0]), "v"(bva[0][0][1]), "v"(bva[0][1][1]), "v"(bva[0][2][1]), "v"(bva[0][3][1]), "v"(bva[1][0][1]), "v"(bva[1][1][1]), "v"(bva[1][2][1]), "v"(bva[1][3][1]));
.Lrp_gen_p5:
	v_lshl_or_b32 v255, s12, 8, v238
	v_lshl_add_u32 v235, s57, 8, v1
	v_lshlrev_b32_e32 v255, 1, v255
	v_lshl_add_u32 v255, v235, 11, v255
	s_mov_b64 s[84:85], s[20:21]
	global_load_dwordx4 v[242:245], v255, s[84:85]
	global_load_dwordx4 v[208:211], v255, s[84:85] offset:256
	s_add_u32 s84, s20, 0x8000
	s_addc_u32 s85, s21, 0
	global_load_dwordx4 v[212:215], v255, s[84:85]
	global_load_dwordx4 v[216:219], v255, s[84:85] offset:256
	s_add_u32 s84, s20, 0x10000
	s_addc_u32 s85, s21, 0
	global_load_dwordx4 v[220:223], v255, s[84:85]
	global_load_dwordx4 v[224:227], v255, s[84:85] offset:256
	s_add_u32 s84, s20, 0x18000
	s_addc_u32 s85, s21, 0
	global_load_dwordx4 v[228:231], v255, s[84:85]
	global_load_dwordx4 v[232:235], v255, s[84:85] offset:256
	s_add_u32 s84, s20, 0x40000
	s_addc_u32 s85, s21, 0
	global_load_dwordx4 v[246:249], v255, s[84:85]
	global_load_dwordx4 v[250:253], v255, s[84:85] offset:256

; __device__ __forceinline__ u32x4 pack8(const f32x4 a, const f32x4 b) { u32x4 w; w.x = cvt_pk_bf16(a[0], a[1]); w.y = cvt_pk_bf16(a[2], a[3]); w.z = cvt_pk_bf16(b[0], b[1]); w.w = cvt_pk_bf16(b[2], b[3]); return w; }
;     __device__ __forceinline__ void operator()(const f32x4 (&acc)[2][2][4][2], const Unit& u, int wr, int wc, int fr, int fq) const {
;     ...
;         const int row0 = u.pm * BM + wr * 64 + fr, col0 = u.pn * BM + wc * 32 + 8 * fq;
;         u32x4 bva[2][4][2];
; #pragma unroll
;         for (int ai = 0; ai < 2; ++ai)
; #pragma unroll
;             for (int m = 0; m < 4; ++m)
; #pragma unroll
;                 for (int bj = 0; bj < 2; ++bj) bva[ai][m][bj] = *(const u32x4*)(Xb + (size_t)(row0 + ai * HALF + m * 16) * DM + col0 + bj * HALF);
;         asm volatile("" :: "v"(bva[0][0][0]), "v"(bva[0][1][0]), "v"(bva[0][2][0]), "v"(bva[0][3][0]), "v"(bva[1][0][0]), "v"(bva[1][1][0]), "v"(bva[1][2][0]), "v"(bva[1][3][0]), "v"(bva[0][0][1]), "v"(bva[0][1][1]), "v"(bva[0][2][1]), "v"(bva[0][3][1]), "v"(bva[1][0][1]), "v"(bva[1][1][1]), "v"(bva[1][2][1]), "v"(bva[1][3][1]));
; #pragma unroll
;         for (int ai = 0; ai < 2; ++ai) {
; #pragma unroll
;             for (int m = 0; m < 4; ++m) { const int row = row0 + ai * HALF + m * 16; float ss = 0.f;
; #pragma unroll
;                 for (int bj = 0; bj < 2; ++bj) { const size_t off = (size_t)row * DM + col0 + bj * HALF; const u32x4 b = bva[ai][m][bj];
;                     f32x4 x0 = (f32x4){__builtin_bit_cast(float, b.x << 16), __builtin_bit_cast(float, b.x & 0xffff0000u), __builtin_bit_cast(float, b.y << 16), __builtin_bit_cast(float, b.y & 0xffff0000u)};
;                     f32x4 x1 = (f32x4){__builtin_bit_cast(float, b.z << 16), __builtin_bit_cast(float, b.z & 0xffff0000u), __builtin_bit_cast(float, b.w << 16), __builtin_bit_cast(float, b.w & 0xffff0000u)};
;                     x0 += acc[ai][bj][m][0]; x1 += acc[ai][bj][m][1];
;                     ss += (x0[0] * x0[0] + x0[1] * x0[1]) + (x0[2] * x0[2] + x0[3] * x0[3]) + (x1[0] * x1[0] + x1[1] * x1[1]) + (x1[2] * x1[2] + x1[3] * x1[3]);
;                     *(u32x4*)(Xb + off) = pack8(x0, x1); }
;                 ss = sum_fq(ss);
;                 if (fq == 0) SS[(size_t)row * 16 + u.pn * 4 + wc] = ss; }
.LBB0_895:
	s_waitcnt vmcnt(0)
	v_mov_b32_e32 v186, v208
	v_mov_b32_e32 v187, v209
	v_mov_b32_e32 v188, v210
	v_mov_b32_e32 v189, v211
	v_mov_b32_e32 v182, v212
	v_mov_b32_e32 v183, v213
	v_mov_b32_e32 v184, v214
	v_mov_b32_e32 v185, v215
	v_mov_b32_e32 v178, v216
	v_mov_b32_e32 v179, v217
	v_mov_b32_e32 v180, v218
	v_mov_b32_e32 v181, v219
	v_mov_b32_e32 v174, v220
	v_mov_b32_e32 v175, v221
	v_mov_b32_e32 v176, v222
	v_mov_b32_e32 v177, v223
	v_mov_b32_e32 v170, v224
	v_mov_b32_e32 v171, v225
	v_mov_b32_e32 v172, v226
	v_mov_b32_e32 v173, v227
	v_mov_b32_e32 v166, v228
	v_mov_b32_e32 v167, v229
	v_mov_b32_e32 v168, v230
	v_mov_b32_e32 v169, v231
	v_mov_b32_e32 v162, v232
	v_mov_b32_e32 v163, v233
	v_mov_b32_e32 v164, v234
	v_mov_b32_e32 v165, v235
	v_mov_b32_e32 v150, v246
	v_mov_b32_e32 v151, v247
	v_mov_b32_e32 v152, v248
	v_mov_b32_e32 v153, v249
	v_mov_b32_e32 v146, v250
	v_mov_b32_e32 v147, v251
	v_mov_b32_e32 v148, v252
	v_mov_b32_e32 v149, v253
	v_lshl_or_b32 v206, s12, 8, v238
	v_lshl_add_u32 v234, s57, 8, v1
	v_ashrrev_i32_e32 v207, 31, v206
	v_lshlrev_b64 v[246:247], 1, v[206:207]
	v_ashrrev_i32_e32 v235, 31, v234
	v_or_b32_e32 v230, 16, v234
	v_lshl_add_u64 v[98:99], s[20:21], 0, v[246:247]
	v_lshlrev_b64 v[248:249], 11, v[234:235]
	v_ashrrev_i32_e32 v231, 31, v230
	v_or_b32_e32 v226, 32, v234
	v_lshl_add_u64 v[100:101], v[98:99], 0, v[248:249]
	v_lshlrev_b64 v[232:233], 11, v[230:231]
	v_ashrrev_i32_e32 v227, 31, v226
	v_or_b32_e32 v222, 48, v234
	v_lshl_add_u64 v[100:101], v[98:99], 0, v[232:233]
	v_lshlrev_b64 v[228:229], 11, v[226:227]
	v_ashrrev_i32_e32 v223, 31, v222
	v_add_u32_e32 v218, 0x80, v234
	v_lshl_add_u64 v[100:101], v[98:99], 0, v[228:229]
	v_lshlrev_b64 v[224:225], 11, v[222:223]
	v_ashrrev_i32_e32 v219, 31, v218
	v_add_u32_e32 v214, 0x90, v234
	v_lshl_add_u64 v[100:101], v[98:99], 0, v[224:225]
	v_lshlrev_b64 v[220:221], 11, v[218:219]
	v_ashrrev_i32_e32 v215, 31, v214
	v_add_u32_e32 v210, 0xa0, v234
	v_add_u32_e32 v204, 0xb0, v234
	v_lshl_add_u64 v[100:101], v[98:99], 0, v[220:221]
	v_lshlrev_b64 v[216:217], 11, v[214:215]
	v_ashrrev_i32_e32 v211, 31, v210
	v_ashrrev_i32_e32 v205, 31, v204
	v_lshl_add_u64 v[100:101], v[98:99], 0, v[216:217]
	v_lshlrev_b64 v[212:213], 11, v[210:211]
	v_lshlrev_b64 v[208:209], 11, v[204:205]
	global_load_dwordx4 v[142:145], v[100:101], off
	global_load_dwordx4 v[138:141], v[100:101], off offset:256
	v_lshl_add_u64 v[100:101], v[98:99], 0, v[212:213]
	v_lshl_add_u64 v[98:99], v[98:99], 0, v[208:209]
	global_load_dwordx4 v[134:137], v[100:101], off
	global_load_dwordx4 v[122:125], v[100:101], off offset:256
	global_load_dwordx4 v[110:113], v[98:99], off
	s_nop 0
	global_load_dwordx4 v[98:101], v[98:99], off offset:256
	s_lshl_b32 s34, s12, 2
	s_ashr_i32 s35, s34, 31
	v_lshlrev_b32_e32 v250, 16, v242
	v_and_b32_e32 v251, 0xffff0000, v242
	v_lshlrev_b32_e32 v242, 16, v243
	v_and_b32_e32 v243, 0xffff0000, v243
	v_lshlrev_b32_e32 v252, 16, v244
	v_and_b32_e32 v253, 0xffff0000, v244
	v_lshlrev_b32_e32 v244, 16, v245
	v_and_b32_e32 v245, 0xffff0000, v245
	v_pk_add_f32 v[160:161], v[160:161], v[242:243]
	v_pk_add_f32 v[158:159], v[158:159], v[250:251]
	v_pk_add_f32 v[242:243], v[156:157], v[244:245]
	v_pk_add_f32 v[156:157], v[154:155], v[252:253]
	v_mul_f32_e32 v154, v159, v159
	v_mul_f32_e32 v155, v161, v161
	v_fmac_f32_e32 v154, v158, v158
	v_fmac_f32_e32 v155, v160, v160
	v_add_f32_e32 v154, v154, v155
	v_mul_f32_e32 v155, v157, v157
	v_fmac_f32_e32 v155, v156, v156
	v_add_f32_e32 v154, v155, v154
	v_mul_f32_e32 v155, v243, v243
	v_fmac_f32_e32 v155, v242, v242
	v_add_f32_e32 v244, v155, v154
	v_cvt_pk_bf16_f32 v154, v158, v159
	v_lshl_add_u64 v[158:159], s[20:21], 0, v[248:249]
	v_cvt_pk_bf16_f32 v155, v160, v161
	v_cvt_pk_bf16_f32 v156, v156, v157
	v_cvt_pk_bf16_f32 v157, v242, v243
	v_lshl_add_u64 v[158:159], v[158:159], 0, v[246:247]
	global_store_dwordx4 v[158:159], v[154:157], off
	v_lshlrev_b32_e32 v160, 16, v188
	v_and_b32_e32 v161, 0xffff0000, v188
	v_lshlrev_b32_e32 v154, 16, v186
	v_and_b32_e32 v155, 0xffff0000, v186
	v_lshlrev_b32_e32 v156, 16, v187
	v_and_b32_e32 v157, 0xffff0000, v187
	v_lshlrev_b32_e32 v186, 16, v189
	v_and_b32_e32 v187, 0xffff0000, v189
	v_pk_add_f32 v[132:133], v[132:133], v[156:157]
	v_pk_add_f32 v[130:131], v[130:131], v[154:155]
	v_pk_add_f32 v[154:155], v[128:129], v[186:187]
	v_pk_add_f32 v[128:129], v[126:127], v[160:161]
	v_mul_f32_e32 v126, v131, v131
	v_mul_f32_e32 v127, v133, v133
	v_fmac_f32_e32 v126, v130, v130
	v_fmac_f32_e32 v127, v132, v132
	v_add_f32_e32 v126, v126, v127
	v_mul_f32_e32 v127, v129, v129
	v_fmac_f32_e32 v127, v128, v128
	v_add_f32_e32 v126, v127, v126
	v_mul_f32_e32 v127, v155, v155
	v_fmac_f32_e32 v127, v154, v154
	v_add_f32_e32 v126, v127, v126
	v_add_f32_e32 v156, v244, v126
	v_cvt_pk_bf16_f32 v126, v130, v131
	v_cvt_pk_bf16_f32 v127, v132, v133
	v_cvt_pk_bf16_f32 v128, v128, v129
	v_cvt_pk_bf16_f32 v129, v154, v155
	global_store_dwordx4 v[158:159], v[126:129], off offset:256
	s_nop 1
	v_mov_b32_e32 v126, v156
	s_nop 1
	v_permlane32_swap_b32_e32 v156, v126
	v_add_f32_e32 v126, v156, v126
	v_mov_b32_e32 v127, v126
	s_nop 1
	v_permlane16_swap_b32_e32 v126, v127
	s_and_saveexec_b64 s[36:37], s[2:3]
	s_cbranch_execz .LBB0_897
	v_add_f32_e32 v128, v126, v127
	v_lshlrev_b64 v[126:127], 6, v[234:235]
	v_lshl_add_u64 v[126:127], s[6:7], 0, v[126:127]
	v_lshl_add_u64 v[126:127], s[34:35], 2, v[126:127]
	s_lshl_b32 s12, s45, 2
	v_lshl_add_u64 v[126:127], v[126:127], 0, s[12:13]
	global_store_dword v[126:127], v128, off

; __device__ __forceinline__ u32x4 pack8(const f32x4 a, const f32x4 b) { u32x4 w; w.x = cvt_pk_bf16(a[0], a[1]); w.y = cvt_pk_bf16(a[2], a[3]); w.z = cvt_pk_bf16(b[0], b[1]); w.w = cvt_pk_bf16(b[2], b[3]); return w; }
;     __device__ __forceinline__ void operator()(const f32x4 (&acc)[2][2][4][2], const Unit& u, int wr, int wc, int fr, int fq) const {
;     ...
;             for (int m = 0; m < 4; ++m) { const int row = row0 + ai * HALF + m * 16; float ss = 0.f;
; #pragma unroll
;                 for (int bj = 0; bj < 2; ++bj) { const size_t off = (size_t)row * DM + col0 + bj * HALF; const u32x4 b = bva[ai][m][bj];
;                     f32x4 x0 = (f32x4){__builtin_bit_cast(float, b.x << 16), __builtin_bit_cast(float, b.x & 0xffff0000u), __builtin_bit_cast(float, b.y << 16), __builtin_bit_cast(float, b.y & 0xffff0000u)};
;                     f32x4 x1 = (f32x4){__builtin_bit_cast(float, b.z << 16), __builtin_bit_cast(float, b.z & 0xffff0000u), __builtin_bit_cast(float, b.w << 16), __builtin_bit_cast(float, b.w & 0xffff0000u)};
;                     x0 += acc[ai][bj][m][0]; x1 += acc[ai][bj][m][1];
;                     ss += (x0[0] * x0[0] + x0[1] * x0[1]) + (x0[2] * x0[2] + x0[3] * x0[3]) + (x1[0] * x1[0] + x1[1] * x1[1]) + (x1[2] * x1[2] + x1[3] * x1[3]);
;                     *(u32x4*)(Xb + off) = pack8(x0, x1); }
;                 ss = sum_fq(ss);
;                 if (fq == 0) SS[(size_t)row * 16 + u.pn * 4 + wc] = ss; }
.LBB0_905:
	s_or_b64 exec, exec, s[36:37]
	s_waitcnt vmcnt(10)
	v_lshlrev_b32_e32 v50, 16, v142
	v_and_b32_e32 v51, 0xffff0000, v142
	v_lshlrev_b32_e32 v52, 16, v143
	v_and_b32_e32 v53, 0xffff0000, v143
	v_lshlrev_b32_e32 v54, 16, v144
	v_and_b32_e32 v55, 0xffff0000, v144
	v_lshlrev_b32_e32 v56, 16, v145
	v_and_b32_e32 v57, 0xffff0000, v145
	v_pk_add_f32 v[48:49], v[48:49], v[52:53]
	v_pk_add_f32 v[46:47], v[46:47], v[50:51]
	v_pk_add_f32 v[50:51], v[44:45], v[56:57]
	v_pk_add_f32 v[44:45], v[42:43], v[54:55]
	v_mul_f32_e32 v42, v47, v47
	v_mul_f32_e32 v43, v49, v49
	v_fmac_f32_e32 v42, v46, v46
	v_fmac_f32_e32 v43, v48, v48
	v_add_f32_e32 v42, v42, v43
	v_mul_f32_e32 v43, v45, v45
	v_fmac_f32_e32 v43, v44, v44
	v_add_f32_e32 v42, v43, v42
	v_mul_f32_e32 v43, v51, v51
	v_fmac_f32_e32 v43, v50, v50
	v_add_f32_e32 v52, v43, v42
	v_cvt_pk_bf16_f32 v42, v46, v47
	v_lshl_add_u64 v[46:47], s[20:21], 0, v[216:217]
	v_cvt_pk_bf16_f32 v43, v48, v49
	v_cvt_pk_bf16_f32 v44, v44, v45
	v_cvt_pk_bf16_f32 v45, v50, v51
	v_lshl_add_u64 v[46:47], v[206:207], 1, v[46:47]
	global_store_dwordx4 v[46:47], v[42:45], off
	v_lshlrev_b32_e32 v48, 16, v140
	v_and_b32_e32 v49, 0xffff0000, v140
	v_lshlrev_b32_e32 v42, 16, v138
	v_and_b32_e32 v43, 0xffff0000, v138
	v_lshlrev_b32_e32 v44, 16, v139
	v_and_b32_e32 v45, 0xffff0000, v139
	v_lshlrev_b32_e32 v50, 16, v141
	v_and_b32_e32 v51, 0xffff0000, v141
	v_pk_add_f32 v[40:41], v[40:41], v[44:45]
	v_pk_add_f32 v[38:39], v[38:39], v[42:43]
	v_pk_add_f32 v[42:43], v[36:37], v[50:51]
	v_pk_add_f32 v[36:37], v[34:35], v[48:49]
	v_mul_f32_e32 v34, v39, v39
	v_mul_f32_e32 v35, v41, v41
	v_fmac_f32_e32 v34, v38, v38
	v_fmac_f32_e32 v35, v40, v40
	v_add_f32_e32 v34, v34, v35
	v_mul_f32_e32 v35, v37, v37
	v_fmac_f32_e32 v35, v36, v36
	v_add_f32_e32 v34, v35, v34
	v_mul_f32_e32 v35, v43, v43
	v_fmac_f32_e32 v35, v42, v42
	v_add_f32_e32 v34, v35, v34
	v_add_f32_e32 v44, v52, v34
	v_cvt_pk_bf16_f32 v34, v38, v39
	v_cvt_pk_bf16_f32 v35, v40, v41
	v_cvt_pk_bf16_f32 v36, v36, v37
	v_cvt_pk_bf16_f32 v37, v42, v43
	global_store_dwordx4 v[46:47], v[34:37], off offset:256
	s_nop 1
	v_mov_b32_e32 v34, v44
	s_nop 1
	v_permlane32_swap_b32_e32 v44, v34
	v_add_f32_e32 v34, v44, v34
	v_mov_b32_e32 v35, v34
	s_nop 1
	v_permlane16_swap_b32_e32 v34, v35
	s_and_saveexec_b64 s[36:37], s[2:3]
	s_cbranch_execz .LBB0_907
	v_add_f32_e32 v36, v34, v35
	v_lshlrev_b64 v[34:35], 6, v[214:215]
	v_lshl_add_u64 v[34:35], s[6:7], 0, v[34:35]
	v_lshl_add_u64 v[34:35], s[34:35], 2, v[34:35]
	s_lshl_b32 s12, s45, 2
	v_lshl_add_u64 v[34:35], v[34:35], 0, s[12:13]
	global_store_dword v[34:35], v36, off
